# final RMSNorm fused into the gate-GEMM epilogue, register-resident: h3 kept in the accumulator registers across a 16-workgroup row-tile rendezvous, scaled and stored once; phase 9 and its seam removed
# speedup vs baseline: 1.0141x; 1.0132x over previous
; #define PG8_STAGE(bufoff, gbase, voff) do { _Pragma("unroll") for (int _i = 0; _i < 2; ++_i) \
;         __builtin_amdgcn_global_load_lds((const unsigned*)((const char*)(gbase) + (voff)[_i]), (PG8_LAS unsigned*)(lds + (bufoff) + ldsw + _i * 8192), 16, 0, 0); } while (0)
; #define PG8_WAIT_V(n) asm volatile("s_waitcnt vmcnt(" #n ")" ::: "memory")
; #define PG8_BAR __builtin_amdgcn_s_barrier()
;     __host__ __device__ bool next(int i, Unit& u) const {
;     ...
;         const int nig = wgm * nN, gid = wgid / nig, fm = gid * wgm, gsz = (nM - fm) < wgm ? (nM - fm) : wgm;
;         u.pm = fm + ((wgid % nig) % gsz); u.pn = (wgid % nig) / gsz; return true;
; template <class Epi, class Sched, bool ALIGN_EPI = false, bool SP2 = false>
; __device__ __forceinline__ void gemm_phase(PG8_LAS unsigned char* lds, const Gemm g, const Sched& S, const Epi& E) {
;     ...
;     const char* cA = (const char*)g.A + (size_t)cur.pm * tstepA; const char* cB = (const char*)g.Bt + (size_t)cur.pn * tstep;
;     S.a_ready(cur);
;     if constexpr (SP2) {
;         PG8_STAGE(PG8_SB(0, 0), cB, voffB); PG8_STAGE(PG8_SB(0, 1), cB + hstep, voffB); PG8_STAGE(PG8_SA(0, 0), cA, voffA); PG8_STAGE(PG8_SA(0, 1), cA + hstep, voffA);
;         if (wr == 1) PG8_BAR;
;         PG8_WAIT_V(2); PG8_BAR;
;         PG8_STAGE(PG8_SB(1, 0), cB + kstep, voffB); PG8_STAGE(PG8_SA(1, 0), cA + kstep, voffA); PG8_STAGE(PG8_SB(1, 1), cB + hstep + kstep, voffB);
;         PG8_WAIT_V(6); PG8_BAR;
;     } else {
;         PG8_STAGE(PG8_SB(0, 0), cB, voffB); PG8_STAGE(PG8_SA(0, 0), cA, voffA); PG8_STAGE(PG8_SB(0, 1), cB + hstep, voffB); PG8_STAGE(PG8_SA(0, 1), cA + hstep, voffA);
;         if (wr == 1) PG8_BAR;
;         PG8_WAIT_V(4); PG8_BAR;
;         PG8_STAGE(PG8_SB(1, 0), cB + kstep, voffB); PG8_STAGE(PG8_SA(1, 0), cA + kstep, voffA); PG8_STAGE(PG8_SB(1, 1), cB + hstep + kstep, voffB);
;         PG8_WAIT_V(6); PG8_BAR;
.LBB0_1444:
	s_load_dwordx2 s[18:19], s[6:7], 0x98
	s_andn2_b64 vcc, exec, s[8:9]
	s_cbranch_vccnz .LBB0_1480
	s_and_b32 s100, s10, 7
	s_lshr_b32 s101, s46, 2
	s_andn2_b32 s10, s10, 7
	s_lshl_b32 s101, s101, 1
	s_add_i32 s10, s10, s101
	s_and_b32 s101, s100, 1
	s_add_i32 s10, s10, s101
	s_lshr_b32 s100, s100, 1
	s_and_b32 s46, s46, 3
	s_lshl_b32 s46, s46, 2
	s_add_i32 s46, s46, s100
	s_waitcnt lgkmcnt(0)
	s_add_u32 s3, s14, 0x21a00000
	v_lshlrev_b32_e32 v1, 4, v0
	s_addc_u32 s37, s15, 0
	v_and_b32_e32 v2, 32, v0
	v_or_b32_e32 v13, 0x2000, v1
	s_add_u32 s54, s14, 0x17000000
	v_bfe_u32 v12, v0, 2, 4
	v_bitop3_b32 v10, v1, v2, 48 bitop3:0x6c
	v_lshrrev_b32_e32 v1, 7, v13
	s_movk_i32 s5, 0x70
	s_addc_u32 s55, s15, 0
	v_and_or_b32 v1, v1, s5, v12
	s_lshr_b32 s5, s1, 6
	s_ashr_i32 s11, s10, 31
	s_ashr_i32 s47, s46, 31
	s_lshr_b32 s4, s1, 8
	s_lshl_b32 s56, s5, 10
	s_lshl_b64 s[6:7], s[10:11], 20
	s_lshl_b64 s[8:9], s[46:47], 20
	v_and_b32_e32 v11, 64, v0
	v_lshrrev_b32_e32 v3, 3, v0
	s_add_u32 s50, s54, s8
	v_or_b32_e32 v2, v10, v11
	v_and_or_b32 v3, v3, 48, v12
	s_addc_u32 s51, s55, s9
	s_add_i32 s47, s56, 0
	v_lshl_or_b32 v158, v3, 12, v2
	s_add_i32 m0, s47, 0x10000
	v_lshl_or_b32 v160, v1, 12, v2
	global_load_lds_dwordx4 v158, s[50:51]
	s_add_i32 m0, s47, 0x12000
	s_add_u32 s8, s50, 0x80000
	global_load_lds_dwordx4 v160, s[50:51]
	s_addc_u32 s9, s51, 0
	s_add_i32 m0, s47, 0x14000
	v_mov_b32_e32 v159, 0
	global_load_lds_dwordx4 v158, s[8:9]
	s_add_i32 m0, s47, 0x16000
	s_add_u32 s48, s3, s6
	s_addc_u32 s49, s37, s7
	s_add_i32 s57, s47, 0x2000
	global_load_lds_dwordx4 v160, s[8:9]
	s_mov_b32 m0, s47
	s_add_u32 s6, s48, 0x80000
	global_load_lds_dwordx4 v158, s[48:49]
	s_mov_b32 m0, s57
	s_addc_u32 s7, s49, 0
	s_add_i32 s58, s47, 0x4000
	global_load_lds_dwordx4 v160, s[48:49]
	s_mov_b32 m0, s58
	s_add_i32 s59, s47, 0x6000
	global_load_lds_dwordx4 v158, s[6:7]
	s_mov_b32 m0, s59
	v_mov_b32_e32 v161, v159
	global_load_lds_dwordx4 v160, s[6:7]
	s_cmp_eq_u32 s4, 1
	s_mov_b32 s60, 0
	v_lshl_add_u64 v[8:9], s[50:51], 0, v[158:159]
	v_lshl_add_u64 v[6:7], s[50:51], 0, v[160:161]
	v_lshl_add_u64 v[2:3], s[48:49], 0, v[158:159]
	s_cselect_b64 s[20:21], -1, 0
	s_cmp_lg_u32 s4, 1
	v_lshl_add_u64 v[4:5], s[48:49], 0, v[160:161]
	s_cbranch_scc1 .LBB0_1447
	s_barrier

;     __host__ __device__ bool next(int i, Unit& u) const {
;     ...
;         const int nig = wgm * nN, gid = wgid / nig, fm = gid * wgm, gsz = (nM - fm) < wgm ? (nM - fm) : wgm;
;         u.pm = fm + ((wgid % nig) % gsz); u.pn = (wgid % nig) / gsz; return true;
; template <class Epi, class Sched, bool ALIGN_EPI = false, bool SP2 = false>
; __device__ __forceinline__ void gemm_phase(PG8_LAS unsigned char* lds, const Gemm g, const Sched& S, const Epi& E) {
;     ...
; #pragma unroll
;         for (int a = 0; a < 2; ++a)
; #pragma unroll
;             for (int b = 0; b < 2; ++b)
; #pragma unroll
;                 for (int m = 0; m < 4; ++m)
; #pragma unroll
;                     for (int n = 0; n < 2; ++n) acc[a][b][m][n] = (f32x4){0.f, 0.f, 0.f, 0.f};
;         cur = nxt; cA = nA; cB = nB; ++ui;
.LBB0_1456:
	s_and_b32 s100, s40, 7
	s_lshr_b32 s101, s38, 2
	s_andn2_b32 s40, s40, 7
	s_lshl_b32 s101, s101, 1
	s_add_i32 s40, s40, s101
	s_and_b32 s101, s100, 1
	s_add_i32 s40, s40, s101
	s_lshr_b32 s100, s100, 1
	s_and_b32 s38, s38, 3
	s_lshl_b32 s38, s38, 2
	s_add_i32 s38, s38, s100
	s_ashr_i32 s41, s40, 31
	s_lshl_b64 s[4:5], s[40:41], 20
	s_add_u32 s42, s3, s4
	s_addc_u32 s43, s37, s5
	s_and_b64 s[4:5], s[8:9], exec
	s_cselect_b32 s1, s43, s49
	s_cselect_b32 s4, s42, s48
	s_ashr_i32 s39, s38, 31
	s_lshl_b64 s[44:45], s[38:39], 20
	s_add_u32 s44, s54, s44
	s_addc_u32 s45, s55, s45
	s_and_b64 s[52:53], s[8:9], exec
	s_cselect_b32 s5, s45, s51
	s_cselect_b32 s11, s44, s50
	s_add_u32 s48, s48, 0x80080
	s_addc_u32 s49, s49, 0
	s_add_u32 s33, s50, 0x100
	v_mov_b32_e32 v2, 0
	s_addc_u32 s39, s51, 0
	s_mov_b32 s41, -2
	s_waitcnt lgkmcnt(0)
	v_mov_b32_e32 v3, v2
	v_mov_b32_e32 v4, v2
	v_mov_b32_e32 v5, v2
	v_mov_b32_e32 v6, v2
	v_mov_b32_e32 v7, v2
	v_mov_b32_e32 v8, v2
	v_mov_b32_e32 v9, v2
	v_mov_b32_e32 v18, v2
	v_mov_b32_e32 v19, v2
	v_mov_b32_e32 v20, v2
	v_mov_b32_e32 v21, v2
	v_mov_b32_e32 v22, v2
	v_mov_b32_e32 v23, v2
	v_mov_b32_e32 v24, v2
	v_mov_b32_e32 v25, v2
	v_mov_b32_e32 v34, v2
	v_mov_b32_e32 v35, v2
	v_mov_b32_e32 v36, v2
	v_mov_b32_e32 v37, v2
	v_mov_b32_e32 v38, v2
	v_mov_b32_e32 v39, v2
	v_mov_b32_e32 v40, v2
	v_mov_b32_e32 v41, v2
	v_mov_b32_e32 v62, v2
	v_mov_b32_e32 v63, v2
	v_mov_b32_e32 v64, v2
	v_mov_b32_e32 v65, v2
	v_mov_b32_e32 v70, v2
	v_mov_b32_e32 v71, v2
	v_mov_b32_e32 v72, v2
	v_mov_b32_e32 v73, v2
	v_mov_b32_e32 v10, v2
	v_mov_b32_e32 v11, v2
	v_mov_b32_e32 v12, v2
	v_mov_b32_e32 v13, v2
	v_mov_b32_e32 v14, v2
	v_mov_b32_e32 v15, v2
	v_mov_b32_e32 v16, v2
	v_mov_b32_e32 v17, v2
	v_mov_b32_e32 v26, v2
	v_mov_b32_e32 v27, v2
	v_mov_b32_e32 v28, v2
	v_mov_b32_e32 v29, v2
	v_mov_b32_e32 v30, v2
	v_mov_b32_e32 v31, v2
	v_mov_b32_e32 v32, v2
	v_mov_b32_e32 v33, v2
	v_mov_b32_e32 v42, v2
	v_mov_b32_e32 v43, v2
	v_mov_b32_e32 v44, v2
	v_mov_b32_e32 v45, v2
	v_mov_b32_e32 v46, v2
	v_mov_b32_e32 v47, v2
	v_mov_b32_e32 v48, v2
	v_mov_b32_e32 v49, v2
	v_mov_b32_e32 v74, v2
	v_mov_b32_e32 v75, v2
	v_mov_b32_e32 v76, v2
	v_mov_b32_e32 v77, v2
	v_mov_b32_e32 v78, v2
	v_mov_b32_e32 v79, v2
	v_mov_b32_e32 v80, v2
	v_mov_b32_e32 v81, v2
	v_mov_b32_e32 v82, v2
	v_mov_b32_e32 v83, v2
	v_mov_b32_e32 v84, v2
	v_mov_b32_e32 v85, v2
	v_mov_b32_e32 v86, v2
	v_mov_b32_e32 v87, v2
	v_mov_b32_e32 v88, v2
	v_mov_b32_e32 v89, v2
	v_mov_b32_e32 v98, v2
	v_mov_b32_e32 v99, v2
	v_mov_b32_e32 v100, v2
	v_mov_b32_e32 v101, v2
	v_mov_b32_e32 v102, v2
	v_mov_b32_e32 v103, v2
	v_mov_b32_e32 v104, v2
	v_mov_b32_e32 v105, v2
	v_mov_b32_e32 v114, v2
	v_mov_b32_e32 v115, v2
	v_mov_b32_e32 v116, v2
	v_mov_b32_e32 v117, v2
	v_mov_b32_e32 v118, v2
	v_mov_b32_e32 v119, v2
	v_mov_b32_e32 v120, v2
	v_mov_b32_e32 v121, v2
	v_mov_b32_e32 v130, v2
	v_mov_b32_e32 v131, v2
	v_mov_b32_e32 v132, v2
	v_mov_b32_e32 v133, v2
	v_mov_b32_e32 v134, v2
	v_mov_b32_e32 v135, v2
	v_mov_b32_e32 v136, v2
	v_mov_b32_e32 v137, v2
	v_mov_b32_e32 v90, v2
	v_mov_b32_e32 v91, v2
	v_mov_b32_e32 v92, v2
	v_mov_b32_e32 v93, v2
	v_mov_b32_e32 v94, v2
	v_mov_b32_e32 v95, v2
	v_mov_b32_e32 v96, v2
	v_mov_b32_e32 v97, v2
	v_mov_b32_e32 v106, v2
	v_mov_b32_e32 v107, v2
	v_mov_b32_e32 v108, v2
	v_mov_b32_e32 v109, v2
	v_mov_b32_e32 v110, v2
	v_mov_b32_e32 v111, v2
	v_mov_b32_e32 v112, v2
	v_mov_b32_e32 v113, v2
	v_mov_b32_e32 v122, v2
	v_mov_b32_e32 v123, v2
	v_mov_b32_e32 v124, v2
	v_mov_b32_e32 v125, v2
	v_mov_b32_e32 v126, v2
	v_mov_b32_e32 v127, v2
	v_mov_b32_e32 v128, v2
	v_mov_b32_e32 v129, v2
	v_mov_b32_e32 v138, v2
	v_mov_b32_e32 v139, v2
	v_mov_b32_e32 v140, v2
	v_mov_b32_e32 v141, v2
	v_mov_b32_e32 v50, v2
	v_mov_b32_e32 v51, v2
	v_mov_b32_e32 v52, v2
	v_mov_b32_e32 v53, v2

;     __device__ __forceinline__ void operator()(const f32x4 (&acc)[2][2][4][2], const pg8::Unit& u, int wr, int wc, int fr, int fq) const {
;         const int row0 = u.pm * 256 + wr * 64 + fr, col0 = u.pn * 256 + wc * 32 + 8 * fq;
;         f32x4 bv[2][2], sb[2][2];
; #pragma unroll
;         for (int bj = 0; bj < 2; ++bj) { bv[bj][0] = *(const f32x4*)(bg + col0 + bj * 128); bv[bj][1] = *(const f32x4*)(bg + col0 + bj * 128 + 4);
;             sb[bj][0] = *(const f32x4*)(cmax + col0 + bj * 128) * (1.f / 127.f); sb[bj][1] = *(const f32x4*)(cmax + col0 + bj * 128 + 4) * (1.f / 127.f); }
; #pragma unroll
;         for (int ai = 0; ai < 2; ++ai)
; #pragma unroll
;             for (int mp = 0; mp < 2; ++mp) {
;                 u32x4 hr[2][2], pr[2][2]; float q1v[2];
; #pragma unroll
;                 for (int mm = 0; mm < 2; ++mm) { const int row = row0 + ai * 128 + (2 * mp + mm) * 16; q1v[mm] = rss1[row];
; #pragma unroll
;                     for (int bj = 0; bj < 2; ++bj) { const size_t off = (size_t)row * DM + col0 + bj * 128; hr[mm][bj] = *(const u32x4*)(HB + off); pr[mm][bj] = *(const u32x4*)(PP + off); } }
; #pragma unroll
;                 for (int mm = 0; mm < 2; ++mm) { const int m = 2 * mp + mm, row = row0 + ai * 128 + m * 16; f32x4 ssv = {0.f, 0.f, 0.f, 0.f}; const float sa = (QCLIP / 127.f) * sqrtf(q1v[mm] * (1.f / DM) + EPS);
; #pragma unroll
;                     for (int bj = 0; bj < 2; ++bj) { const size_t off = (size_t)row * DM + col0 + bj * 128;
;                         f32x4 p0, p1, x0, x1; unpack8v(pr[mm][bj], p0, p1); unpack8v(hr[mm][bj], x0, x1);
;                         const f32x4 g0 = acc_i2f(acc[ai][bj][m][0]) * (sb[bj][0] * sa) + bv[bj][0], g1 = acc_i2f(acc[ai][bj][m][1]) * (sb[bj][1] * sa) + bv[bj][1];
;                         const f32x4 h0 = x0 + p0 * sigm4(g0), h1 = x1 + p1 * sigm4(g1);
;                         *(f32x4*)(H + off) = h0; *(f32x4*)(H + off + 4) = h1;
;                         ssv = ssv + h0 * h0; ssv = ssv + h1 * h1; }
;                     float ss = (ssv[0] + ssv[1]) + (ssv[2] + ssv[3]);
;                     ss += __shfl_xor(ss, 16); ss += __shfl_xor(ss, 32);
;                     if (fq == 0) unsafeAtomicAdd(rss3 + row, ss); }
;                 asm volatile("" ::: "memory"); }
;     }
.LBB0_1460:
	s_mov_b32 s98, s10
	s_mov_b32 s99, s46
	v_lshlrev_b32_e32 v54, 2, v1
	v_lshlrev_b32_e32 v55, 2, v199
	v_lshlrev_b32_e32 v56, 13, v1
	v_lshlrev_b32_e32 v57, 14, v1
	v_lshl_add_u32 v56, v199, 1, v56
	v_lshl_add_u32 v57, v199, 2, v57
	v_xor_b32_e32 v58, 16, v203
	v_xor_b32_e32 v59, 32, v203
	v_lshlrev_b32_e32 v58, 2, v58
	v_lshlrev_b32_e32 v59, 2, v59
	s_lshl_b32 s48, s99, 10
	s_add_u32 s50, s14, s48
	s_addc_u32 s51, s15, 0
	s_add_u32 s52, s18, s48
	s_addc_u32 s53, s19, 0
	s_lshl_b32 s49, s98, 10
	s_add_u32 s68, s28, s49
	s_addc_u32 s69, s29, 0
	s_add_u32 s70, s26, s49
	s_addc_u32 s71, s27, 0
	s_lshl_b32 s72, s98, 21
	s_lshl_b32 s73, s99, 9
	s_add_u32 s72, s72, s73
	s_add_u32 s86, s22, s72
	s_addc_u32 s87, s23, 0
	s_add_u32 s88, s24, s72
	s_addc_u32 s89, s25, 0
	s_lshl_b32 s72, s98, 22
	s_add_u32 s72, s72, s48
	s_add_u32 s84, s12, s72
	s_addc_u32 s85, s13, 0
	global_load_dwordx4 v[222:225], v55, s[50:51]
	global_load_dwordx4 v[226:229], v55, s[50:51] offset:16
	global_load_dwordx4 v[230:233], v55, s[50:51] offset:512
	global_load_dwordx4 v[234:237], v55, s[50:51] offset:528
	global_load_dwordx4 v[206:209], v55, s[52:53]
	global_load_dwordx4 v[210:213], v55, s[52:53] offset:16
	global_load_dwordx4 v[214:217], v55, s[52:53] offset:512
	global_load_dwordx4 v[218:221], v55, s[52:53] offset:528
	global_load_dword v66, v54, s[68:69]
	global_load_dwordx4 v[238:241], v56, s[86:87]
	global_load_dwordx4 v[242:245], v56, s[86:87] offset:256
	global_load_dwordx4 v[246:249], v56, s[88:89]
	global_load_dwordx4 v[250:253], v56, s[88:89] offset:256
	s_add_u32 s86, s86, 0x20000
	s_addc_u32 s87, s87, 0
	s_add_u32 s88, s88, 0x20000
	s_addc_u32 s89, s89, 0
	global_load_dword v67, v54, s[68:69] offset:64
	global_load_dwordx4 v[170:173], v56, s[86:87]
	global_load_dwordx4 v[174:177], v56, s[86:87] offset:256
	global_load_dwordx4 v[178:181], v56, s[88:89]
	global_load_dwordx4 v[182:185], v56, s[88:89] offset:256
	s_add_u32 s86, s86, 0x20000
	s_addc_u32 s87, s87, 0
	s_add_u32 s88, s88, 0x20000
	s_addc_u32 s89, s89, 0
	s_waitcnt vmcnt(5)
	v_pk_mul_f32 v[222:223], v[222:223], s[36:37] op_sel_hi:[1,0]
	v_pk_mul_f32 v[224:225], v[224:225], s[36:37] op_sel_hi:[1,0]
	v_pk_mul_f32 v[226:227], v[226:227], s[36:37] op_sel_hi:[1,0]
	v_pk_mul_f32 v[228:229], v[228:229], s[36:37] op_sel_hi:[1,0]
	v_pk_mul_f32 v[230:231], v[230:231], s[36:37] op_sel_hi:[1,0]
	v_pk_mul_f32 v[232:233], v[232:233], s[36:37] op_sel_hi:[1,0]
	v_pk_mul_f32 v[234:235], v[234:235], s[36:37] op_sel_hi:[1,0]
	v_pk_mul_f32 v[236:237], v[236:237], s[36:37] op_sel_hi:[1,0]
	v_fmamk_f32 v186, v66, 0x39800000, v204
	v_mul_f32_e32 v187, 0x4f800000, v186
	v_cmp_gt_f32_e32 vcc, s67, v186
	s_nop 1
	v_cndmask_b32_e32 v186, v186, v187, vcc
	v_sqrt_f32_e32 v190, v186
	s_nop 0
	v_add_u32_e32 v191, -1, v190
	v_add_u32_e32 v192, 1, v190
	v_fma_f32 v193, -v191, v190, v186
	v_fma_f32 v187, -v192, v190, v186
	v_cmp_ge_f32_e64 s[10:11], 0, v193
	s_nop 1
	v_cndmask_b32_e64 v190, v190, v191, s[10:11]
	v_cmp_lt_f32_e64 s[10:11], 0, v187
	s_nop 1
	v_cndmask_b32_e64 v190, v190, v192, s[10:11]
	v_mul_f32_e32 v191, 0x37800000, v190
	v_cndmask_b32_e32 v190, v190, v191, vcc
	v_cmp_class_f32_e32 vcc, v186, v205
	s_nop 1
	v_cndmask_b32_e32 v186, v190, v186, vcc
	v_mul_f32_e32 v188, 0x3d112245, v186
	v_cvt_f32_i32_e32 v50, v50
	v_cvt_f32_i32_e32 v51, v51
	v_cvt_f32_i32_e32 v52, v52
	v_cvt_f32_i32_e32 v53, v53
	v_pk_mul_f32 v[142:143], v[222:223], v[188:189] op_sel_hi:[1,0]
	v_pk_mul_f32 v[144:145], v[224:225], v[188:189] op_sel_hi:[1,0]
	v_pk_fma_f32 v[154:155], v[142:143], v[50:51], v[206:207]
	v_pk_fma_f32 v[156:157], v[144:145], v[52:53], v[208:209]
	v_mul_f32_e32 v154, 0xbfb8aa3b, v154
	v_mul_f32_e32 v155, 0xbfb8aa3b, v155
	v_mul_f32_e32 v156, 0xbfb8aa3b, v156
	v_mul_f32_e32 v157, 0xbfb8aa3b, v157
	v_exp_f32_e32 v154, v154
	v_exp_f32_e32 v155, v155
	v_exp_f32_e32 v156, v156
	v_exp_f32_e32 v157, v157
	v_lshlrev_b32_e32 v146, 16, v238
	v_and_b32_e32 v147, 0xffff0000, v238
	v_lshlrev_b32_e32 v148, 16, v239
	v_and_b32_e32 v149, 0xffff0000, v239
	v_add_f32_e32 v154, 1.0, v154
	v_add_f32_e32 v155, 1.0, v155
	v_add_f32_e32 v156, 1.0, v156
	v_add_f32_e32 v157, 1.0, v157
	v_rcp_f32_e32 v154, v154
	v_rcp_f32_e32 v155, v155
	v_rcp_f32_e32 v156, v156
	v_rcp_f32_e32 v157, v157
	v_lshlrev_b32_e32 v150, 16, v246
	v_and_b32_e32 v151, 0xffff0000, v246
	v_lshlrev_b32_e32 v152, 16, v247
	v_and_b32_e32 v153, 0xffff0000, v247
	v_pk_fma_f32 v[50:51], v[154:155], v[150:151], v[146:147]
	v_pk_fma_f32 v[52:53], v[156:157], v[152:153], v[148:149]
	v_pk_mul_f32 v[194:195], v[50:51], v[50:51]
	v_pk_mul_f32 v[196:197], v[52:53], v[52:53]
	v_cvt_f32_i32_e32 v138, v138
	v_cvt_f32_i32_e32 v139, v139
	v_cvt_f32_i32_e32 v140, v140
	v_cvt_f32_i32_e32 v141, v141
	v_pk_mul_f32 v[142:143], v[226:227], v[188:189] op_sel_hi:[1,0]
	v_pk_mul_f32 v[144:145], v[228:229], v[188:189] op_sel_hi:[1,0]
	v_pk_fma_f32 v[154:155], v[142:143], v[138:139], v[210:211]
	v_pk_fma_f32 v[156:157], v[144:145], v[140:141], v[212:213]
	v_mul_f32_e32 v154, 0xbfb8aa3b, v154
	v_mul_f32_e32 v155, 0xbfb8aa3b, v155
	v_mul_f32_e32 v156, 0xbfb8aa3b, v156
	v_mul_f32_e32 v157, 0xbfb8aa3b, v157
	v_exp_f32_e32 v154, v154
	v_exp_f32_e32 v155, v155
	v_exp_f32_e32 v156, v156
	v_exp_f32_e32 v157, v157
	v_lshlrev_b32_e32 v146, 16, v240
	v_and_b32_e32 v147, 0xffff0000, v240
	v_lshlrev_b32_e32 v148, 16, v241
	v_and_b32_e32 v149, 0xffff0000, v241
	v_add_f32_e32 v154, 1.0, v154
	v_add_f32_e32 v155, 1.0, v155
	v_add_f32_e32 v156, 1.0, v156
	v_add_f32_e32 v157, 1.0, v157
	v_rcp_f32_e32 v154, v154
	v_rcp_f32_e32 v155, v155
	v_rcp_f32_e32 v156, v156
	v_rcp_f32_e32 v157, v157
	v_lshlrev_b32_e32 v150, 16, v248
;     __device__ __forceinline__ void operator()(const f32x4 (&acc)[2][2][4][2], const pg8::Unit& u, int wr, int wc, int fr, int fq) const {
;         const int row0 = u.pm * 256 + wr * 64 + fr, col0 = u.pn * 256 + wc * 32 + 8 * fq;
;         f32x4 bv[2][2], sb[2][2];
; #pragma unroll
;         for (int bj = 0; bj < 2; ++bj) { bv[bj][0] = *(const f32x4*)(bg + col0 + bj * 128); bv[bj][1] = *(const f32x4*)(bg + col0 + bj * 128 + 4);
;             sb[bj][0] = *(const f32x4*)(cmax + col0 + bj * 128) * (1.f / 127.f); sb[bj][1] = *(const f32x4*)(cmax + col0 + bj * 128 + 4) * (1.f / 127.f); }
; #pragma unroll
;         for (int ai = 0; ai < 2; ++ai)
; #pragma unroll
;             for (int mp = 0; mp < 2; ++mp) {
;                 u32x4 hr[2][2], pr[2][2]; float q1v[2];
; #pragma unroll
;                 for (int mm = 0; mm < 2; ++mm) { const int row = row0 + ai * 128 + (2 * mp + mm) * 16; q1v[mm] = rss1[row];
; #pragma unroll
;                     for (int bj = 0; bj < 2; ++bj) { const size_t off = (size_t)row * DM + col0 + bj * 128; hr[mm][bj] = *(const u32x4*)(HB + off); pr[mm][bj] = *(const u32x4*)(PP + off); } }
; #pragma unroll
;                 for (int mm = 0; mm < 2; ++mm) { const int m = 2 * mp + mm, row = row0 + ai * 128 + m * 16; f32x4 ssv = {0.f, 0.f, 0.f, 0.f}; const float sa = (QCLIP / 127.f) * sqrtf(q1v[mm] * (1.f / DM) + EPS);
; #pragma unroll
;                     for (int bj = 0; bj < 2; ++bj) { const size_t off = (size_t)row * DM + col0 + bj * 128;
;                         f32x4 p0, p1, x0, x1; unpack8v(pr[mm][bj], p0, p1); unpack8v(hr[mm][bj], x0, x1);
;                         const f32x4 g0 = acc_i2f(acc[ai][bj][m][0]) * (sb[bj][0] * sa) + bv[bj][0], g1 = acc_i2f(acc[ai][bj][m][1]) * (sb[bj][1] * sa) + bv[bj][1];
;                         const f32x4 h0 = x0 + p0 * sigm4(g0), h1 = x1 + p1 * sigm4(g1);
;                         *(f32x4*)(H + off) = h0; *(f32x4*)(H + off + 4) = h1;
;                         ssv = ssv + h0 * h0; ssv = ssv + h1 * h1; }
;                     float ss = (ssv[0] + ssv[1]) + (ssv[2] + ssv[3]);
;                     ss += __shfl_xor(ss, 16); ss += __shfl_xor(ss, 32);
;                     if (fq == 0) unsafeAtomicAdd(rss3 + row, ss); }
;                 asm volatile("" ::: "memory"); }
;     }
	v_and_b32_e32 v151, 0xffff0000, v248
	v_lshlrev_b32_e32 v152, 16, v249
	v_and_b32_e32 v153, 0xffff0000, v249
	v_pk_fma_f32 v[138:139], v[154:155], v[150:151], v[146:147]
	v_pk_fma_f32 v[140:141], v[156:157], v[152:153], v[148:149]
	v_pk_fma_f32 v[194:195], v[138:139], v[138:139], v[194:195]
	v_pk_fma_f32 v[196:197], v[140:141], v[140:141], v[196:197]
	v_cvt_f32_i32_e32 v134, v134
	v_cvt_f32_i32_e32 v135, v135
	v_cvt_f32_i32_e32 v136, v136
	v_cvt_f32_i32_e32 v137, v137
	v_pk_mul_f32 v[142:143], v[230:231], v[188:189] op_sel_hi:[1,0]
	v_pk_mul_f32 v[144:145], v[232:233], v[188:189] op_sel_hi:[1,0]
	v_pk_fma_f32 v[154:155], v[142:143], v[134:135], v[214:215]
	v_pk_fma_f32 v[156:157], v[144:145], v[136:137], v[216:217]
	v_mul_f32_e32 v154, 0xbfb8aa3b, v154
	v_mul_f32_e32 v155, 0xbfb8aa3b, v155
	v_mul_f32_e32 v156, 0xbfb8aa3b, v156
	v_mul_f32_e32 v157, 0xbfb8aa3b, v157
	v_exp_f32_e32 v154, v154
	v_exp_f32_e32 v155, v155
	v_exp_f32_e32 v156, v156
	v_exp_f32_e32 v157, v157
	v_lshlrev_b32_e32 v146, 16, v242
	v_and_b32_e32 v147, 0xffff0000, v242
	v_lshlrev_b32_e32 v148, 16, v243
	v_and_b32_e32 v149, 0xffff0000, v243
	v_add_f32_e32 v154, 1.0, v154
	v_add_f32_e32 v155, 1.0, v155
	v_add_f32_e32 v156, 1.0, v156
	v_add_f32_e32 v157, 1.0, v157
	v_rcp_f32_e32 v154, v154
	v_rcp_f32_e32 v155, v155
	v_rcp_f32_e32 v156, v156
	v_rcp_f32_e32 v157, v157
	v_lshlrev_b32_e32 v150, 16, v250
	v_and_b32_e32 v151, 0xffff0000, v250
	v_lshlrev_b32_e32 v152, 16, v251
	v_and_b32_e32 v153, 0xffff0000, v251
	v_pk_fma_f32 v[134:135], v[154:155], v[150:151], v[146:147]
	v_pk_fma_f32 v[136:137], v[156:157], v[152:153], v[148:149]
	v_pk_fma_f32 v[194:195], v[134:135], v[134:135], v[194:195]
	v_pk_fma_f32 v[196:197], v[136:137], v[136:137], v[196:197]
	v_cvt_f32_i32_e32 v130, v130
	v_cvt_f32_i32_e32 v131, v131
	v_cvt_f32_i32_e32 v132, v132
	v_cvt_f32_i32_e32 v133, v133
	v_pk_mul_f32 v[142:143], v[234:235], v[188:189] op_sel_hi:[1,0]
	v_pk_mul_f32 v[144:145], v[236:237], v[188:189] op_sel_hi:[1,0]
	v_pk_fma_f32 v[154:155], v[142:143], v[130:131], v[218:219]
	v_pk_fma_f32 v[156:157], v[144:145], v[132:133], v[220:221]
	v_mul_f32_e32 v154, 0xbfb8aa3b, v154
	v_mul_f32_e32 v155, 0xbfb8aa3b, v155
	v_mul_f32_e32 v156, 0xbfb8aa3b, v156
	v_mul_f32_e32 v157, 0xbfb8aa3b, v157
	v_exp_f32_e32 v154, v154
	v_exp_f32_e32 v155, v155
	v_exp_f32_e32 v156, v156
	v_exp_f32_e32 v157, v157
	v_lshlrev_b32_e32 v146, 16, v244
	v_and_b32_e32 v147, 0xffff0000, v244
	v_lshlrev_b32_e32 v148, 16, v245
	v_and_b32_e32 v149, 0xffff0000, v245
	v_add_f32_e32 v154, 1.0, v154
	v_add_f32_e32 v155, 1.0, v155
	v_add_f32_e32 v156, 1.0, v156
	v_add_f32_e32 v157, 1.0, v157
	v_rcp_f32_e32 v154, v154
	v_rcp_f32_e32 v155, v155
	v_rcp_f32_e32 v156, v156
	v_rcp_f32_e32 v157, v157
	v_lshlrev_b32_e32 v150, 16, v252
	v_and_b32_e32 v151, 0xffff0000, v252
	v_lshlrev_b32_e32 v152, 16, v253
	v_and_b32_e32 v153, 0xffff0000, v253
	v_pk_fma_f32 v[130:131], v[154:155], v[150:151], v[146:147]
	v_pk_fma_f32 v[132:133], v[156:157], v[152:153], v[148:149]
	v_pk_fma_f32 v[194:195], v[130:131], v[130:131], v[194:195]
	v_pk_fma_f32 v[196:197], v[132:133], v[132:133], v[196:197]
	v_add_f32_e32 v194, v194, v195
	v_add_f32_e32 v196, v196, v197
	v_add_f32_e32 v194, v194, v196
	ds_bpermute_b32 v195, v58, v194
	s_waitcnt lgkmcnt(0)
	v_add_f32_e32 v194, v194, v195
	ds_bpermute_b32 v195, v59, v194
	s_waitcnt lgkmcnt(0)
	v_add_f32_e32 v194, v194, v195
	s_and_saveexec_b64 s[32:33], s[6:7]
	global_atomic_add_f32 v54, v194, s[70:71]
	s_or_b64 exec, exec, s[32:33]
	global_load_dword v66, v54, s[68:69] offset:128
	global_load_dwordx4 v[238:241], v56, s[86:87]
	global_load_dwordx4 v[242:245], v56, s[86:87] offset:256
	global_load_dwordx4 v[246:249], v56, s[88:89]
	global_load_dwordx4 v[250:253], v56, s[88:89] offset:256
	s_add_u32 s86, s86, 0x20000
	s_addc_u32 s87, s87, 0
	s_add_u32 s88, s88, 0x20000
	s_addc_u32 s89, s89, 0
	s_waitcnt vmcnt(6)
	v_fmamk_f32 v186, v67, 0x39800000, v204
	v_mul_f32_e32 v187, 0x4f800000, v186
	v_cmp_gt_f32_e32 vcc, s67, v186
	s_nop 1
	v_cndmask_b32_e32 v186, v186, v187, vcc
	v_sqrt_f32_e32 v190, v186
	s_nop 0
	v_add_u32_e32 v191, -1, v190
	v_add_u32_e32 v192, 1, v190
	v_fma_f32 v193, -v191, v190, v186
	v_fma_f32 v187, -v192, v190, v186
	v_cmp_ge_f32_e64 s[10:11], 0, v193
	s_nop 1
	v_cndmask_b32_e64 v190, v190, v191, s[10:11]
	v_cmp_lt_f32_e64 s[10:11], 0, v187
	s_nop 1
	v_cndmask_b32_e64 v190, v190, v192, s[10:11]
	v_mul_f32_e32 v191, 0x37800000, v190
	v_cndmask_b32_e32 v190, v190, v191, vcc
	v_cmp_class_f32_e32 vcc, v186, v205
	s_nop 1
	v_cndmask_b32_e32 v186, v190, v186, vcc
	v_mul_f32_e32 v188, 0x3d112245, v186
	v_cvt_f32_i32_e32 v126, v126
	v_cvt_f32_i32_e32 v127, v127
	v_cvt_f32_i32_e32 v128, v128
	v_cvt_f32_i32_e32 v129, v129
	v_pk_mul_f32 v[142:143], v[222:223], v[188:189] op_sel_hi:[1,0]
	v_pk_mul_f32 v[144:145], v[224:225], v[188:189] op_sel_hi:[1,0]
	v_pk_fma_f32 v[154:155], v[142:143], v[126:127], v[206:207]
	v_pk_fma_f32 v[156:157], v[144:145], v[128:129], v[208:209]
	v_mul_f32_e32 v154, 0xbfb8aa3b, v154
	v_mul_f32_e32 v155, 0xbfb8aa3b, v155
	v_mul_f32_e32 v156, 0xbfb8aa3b, v156
	v_mul_f32_e32 v157, 0xbfb8aa3b, v157
	v_exp_f32_e32 v154, v154
	v_exp_f32_e32 v155, v155
	v_exp_f32_e32 v156, v156
	v_exp_f32_e32 v157, v157
	v_lshlrev_b32_e32 v146, 16, v170
	v_and_b32_e32 v147, 0xffff0000, v170
	v_lshlrev_b32_e32 v148, 16, v171
	v_and_b32_e32 v149, 0xffff0000, v171
	v_add_f32_e32 v154, 1.0, v154
	v_add_f32_e32 v155, 1.0, v155
	v_add_f32_e32 v156, 1.0, v156
	v_add_f32_e32 v157, 1.0, v157
	v_rcp_f32_e32 v154, v154
	v_rcp_f32_e32 v155, v155
	v_rcp_f32_e32 v156, v156
	v_rcp_f32_e32 v157, v157
	v_lshlrev_b32_e32 v150, 16, v178
;     __device__ __forceinline__ void operator()(const f32x4 (&acc)[2][2][4][2], const pg8::Unit& u, int wr, int wc, int fr, int fq) const {
;         const int row0 = u.pm * 256 + wr * 64 + fr, col0 = u.pn * 256 + wc * 32 + 8 * fq;
;         f32x4 bv[2][2], sb[2][2];
; #pragma unroll
;         for (int bj = 0; bj < 2; ++bj) { bv[bj][0] = *(const f32x4*)(bg + col0 + bj * 128); bv[bj][1] = *(const f32x4*)(bg + col0 + bj * 128 + 4);
;             sb[bj][0] = *(const f32x4*)(cmax + col0 + bj * 128) * (1.f / 127.f); sb[bj][1] = *(const f32x4*)(cmax + col0 + bj * 128 + 4) * (1.f / 127.f); }
; #pragma unroll
;         for (int ai = 0; ai < 2; ++ai)
; #pragma unroll
;             for (int mp = 0; mp < 2; ++mp) {
;                 u32x4 hr[2][2], pr[2][2]; float q1v[2];
; #pragma unroll
;                 for (int mm = 0; mm < 2; ++mm) { const int row = row0 + ai * 128 + (2 * mp + mm) * 16; q1v[mm] = rss1[row];
; #pragma unroll
;                     for (int bj = 0; bj < 2; ++bj) { const size_t off = (size_t)row * DM + col0 + bj * 128; hr[mm][bj] = *(const u32x4*)(HB + off); pr[mm][bj] = *(const u32x4*)(PP + off); } }
; #pragma unroll
;                 for (int mm = 0; mm < 2; ++mm) { const int m = 2 * mp + mm, row = row0 + ai * 128 + m * 16; f32x4 ssv = {0.f, 0.f, 0.f, 0.f}; const float sa = (QCLIP / 127.f) * sqrtf(q1v[mm] * (1.f / DM) + EPS);
; #pragma unroll
;                     for (int bj = 0; bj < 2; ++bj) { const size_t off = (size_t)row * DM + col0 + bj * 128;
;                         f32x4 p0, p1, x0, x1; unpack8v(pr[mm][bj], p0, p1); unpack8v(hr[mm][bj], x0, x1);
;                         const f32x4 g0 = acc_i2f(acc[ai][bj][m][0]) * (sb[bj][0] * sa) + bv[bj][0], g1 = acc_i2f(acc[ai][bj][m][1]) * (sb[bj][1] * sa) + bv[bj][1];
;                         const f32x4 h0 = x0 + p0 * sigm4(g0), h1 = x1 + p1 * sigm4(g1);
;                         *(f32x4*)(H + off) = h0; *(f32x4*)(H + off + 4) = h1;
;                         ssv = ssv + h0 * h0; ssv = ssv + h1 * h1; }
;                     float ss = (ssv[0] + ssv[1]) + (ssv[2] + ssv[3]);
;                     ss += __shfl_xor(ss, 16); ss += __shfl_xor(ss, 32);
;                     if (fq == 0) unsafeAtomicAdd(rss3 + row, ss); }
;                 asm volatile("" ::: "memory"); }
;     }
	v_and_b32_e32 v151, 0xffff0000, v178
	v_lshlrev_b32_e32 v152, 16, v179
	v_and_b32_e32 v153, 0xffff0000, v179
	v_pk_fma_f32 v[126:127], v[154:155], v[150:151], v[146:147]
	v_pk_fma_f32 v[128:129], v[156:157], v[152:153], v[148:149]
	v_pk_mul_f32 v[194:195], v[126:127], v[126:127]
	v_pk_mul_f32 v[196:197], v[128:129], v[128:129]
	v_cvt_f32_i32_e32 v122, v122
	v_cvt_f32_i32_e32 v123, v123
	v_cvt_f32_i32_e32 v124, v124
	v_cvt_f32_i32_e32 v125, v125
	v_pk_mul_f32 v[142:143], v[226:227], v[188:189] op_sel_hi:[1,0]
	v_pk_mul_f32 v[144:145], v[228:229], v[188:189] op_sel_hi:[1,0]
	v_pk_fma_f32 v[154:155], v[142:143], v[122:123], v[210:211]
	v_pk_fma_f32 v[156:157], v[144:145], v[124:125], v[212:213]
	v_mul_f32_e32 v154, 0xbfb8aa3b, v154
	v_mul_f32_e32 v155, 0xbfb8aa3b, v155
	v_mul_f32_e32 v156, 0xbfb8aa3b, v156
	v_mul_f32_e32 v157, 0xbfb8aa3b, v157
	v_exp_f32_e32 v154, v154
	v_exp_f32_e32 v155, v155
	v_exp_f32_e32 v156, v156
	v_exp_f32_e32 v157, v157
	v_lshlrev_b32_e32 v146, 16, v172
	v_and_b32_e32 v147, 0xffff0000, v172
	v_lshlrev_b32_e32 v148, 16, v173
	v_and_b32_e32 v149, 0xffff0000, v173
	v_add_f32_e32 v154, 1.0, v154
	v_add_f32_e32 v155, 1.0, v155
	v_add_f32_e32 v156, 1.0, v156
	v_add_f32_e32 v157, 1.0, v157
	v_rcp_f32_e32 v154, v154
	v_rcp_f32_e32 v155, v155
	v_rcp_f32_e32 v156, v156
	v_rcp_f32_e32 v157, v157
	v_lshlrev_b32_e32 v150, 16, v180
	v_and_b32_e32 v151, 0xffff0000, v180
	v_lshlrev_b32_e32 v152, 16, v181
	v_and_b32_e32 v153, 0xffff0000, v181
	v_pk_fma_f32 v[122:123], v[154:155], v[150:151], v[146:147]
	v_pk_fma_f32 v[124:125], v[156:157], v[152:153], v[148:149]
	v_pk_fma_f32 v[194:195], v[122:123], v[122:123], v[194:195]
	v_pk_fma_f32 v[196:197], v[124:125], v[124:125], v[196:197]
	v_cvt_f32_i32_e32 v118, v118
	v_cvt_f32_i32_e32 v119, v119
	v_cvt_f32_i32_e32 v120, v120
	v_cvt_f32_i32_e32 v121, v121
	v_pk_mul_f32 v[142:143], v[230:231], v[188:189] op_sel_hi:[1,0]
	v_pk_mul_f32 v[144:145], v[232:233], v[188:189] op_sel_hi:[1,0]
	v_pk_fma_f32 v[154:155], v[142:143], v[118:119], v[214:215]
	v_pk_fma_f32 v[156:157], v[144:145], v[120:121], v[216:217]
	v_mul_f32_e32 v154, 0xbfb8aa3b, v154
	v_mul_f32_e32 v155, 0xbfb8aa3b, v155
	v_mul_f32_e32 v156, 0xbfb8aa3b, v156
	v_mul_f32_e32 v157, 0xbfb8aa3b, v157
	v_exp_f32_e32 v154, v154
	v_exp_f32_e32 v155, v155
	v_exp_f32_e32 v156, v156
	v_exp_f32_e32 v157, v157
	v_lshlrev_b32_e32 v146, 16, v174
	v_and_b32_e32 v147, 0xffff0000, v174
	v_lshlrev_b32_e32 v148, 16, v175
	v_and_b32_e32 v149, 0xffff0000, v175
	v_add_f32_e32 v154, 1.0, v154
	v_add_f32_e32 v155, 1.0, v155
	v_add_f32_e32 v156, 1.0, v156
	v_add_f32_e32 v157, 1.0, v157
	v_rcp_f32_e32 v154, v154
	v_rcp_f32_e32 v155, v155
	v_rcp_f32_e32 v156, v156
	v_rcp_f32_e32 v157, v157
	v_lshlrev_b32_e32 v150, 16, v182
	v_and_b32_e32 v151, 0xffff0000, v182
	v_lshlrev_b32_e32 v152, 16, v183
	v_and_b32_e32 v153, 0xffff0000, v183
	v_pk_fma_f32 v[118:119], v[154:155], v[150:151], v[146:147]
	v_pk_fma_f32 v[120:121], v[156:157], v[152:153], v[148:149]
	v_pk_fma_f32 v[194:195], v[118:119], v[118:119], v[194:195]
	v_pk_fma_f32 v[196:197], v[120:121], v[120:121], v[196:197]
	v_cvt_f32_i32_e32 v114, v114
	v_cvt_f32_i32_e32 v115, v115
	v_cvt_f32_i32_e32 v116, v116
	v_cvt_f32_i32_e32 v117, v117
	v_pk_mul_f32 v[142:143], v[234:235], v[188:189] op_sel_hi:[1,0]
	v_pk_mul_f32 v[144:145], v[236:237], v[188:189] op_sel_hi:[1,0]
	v_pk_fma_f32 v[154:155], v[142:143], v[114:115], v[218:219]
	v_pk_fma_f32 v[156:157], v[144:145], v[116:117], v[220:221]
	v_mul_f32_e32 v154, 0xbfb8aa3b, v154
	v_mul_f32_e32 v155, 0xbfb8aa3b, v155
	v_mul_f32_e32 v156, 0xbfb8aa3b, v156
	v_mul_f32_e32 v157, 0xbfb8aa3b, v157
	v_exp_f32_e32 v154, v154
	v_exp_f32_e32 v155, v155
	v_exp_f32_e32 v156, v156
	v_exp_f32_e32 v157, v157
	v_lshlrev_b32_e32 v146, 16, v176
	v_and_b32_e32 v147, 0xffff0000, v176
	v_lshlrev_b32_e32 v148, 16, v177
	v_and_b32_e32 v149, 0xffff0000, v177
	v_add_f32_e32 v154, 1.0, v154
	v_add_f32_e32 v155, 1.0, v155
	v_add_f32_e32 v156, 1.0, v156
	v_add_f32_e32 v157, 1.0, v157
	v_rcp_f32_e32 v154, v154
	v_rcp_f32_e32 v155, v155
	v_rcp_f32_e32 v156, v156
	v_rcp_f32_e32 v157, v157
	v_lshlrev_b32_e32 v150, 16, v184
	v_and_b32_e32 v151, 0xffff0000, v184
	v_lshlrev_b32_e32 v152, 16, v185
	v_and_b32_e32 v153, 0xffff0000, v185
	v_pk_fma_f32 v[114:115], v[154:155], v[150:151], v[146:147]
	v_pk_fma_f32 v[116:117], v[156:157], v[152:153], v[148:149]
	v_pk_fma_f32 v[194:195], v[114:115], v[114:115], v[194:195]
	v_pk_fma_f32 v[196:197], v[116:117], v[116:117], v[196:197]
	v_add_f32_e32 v194, v194, v195
	v_add_f32_e32 v196, v196, v197
	v_add_f32_e32 v194, v194, v196
	ds_bpermute_b32 v195, v58, v194
	s_waitcnt lgkmcnt(0)
	v_add_f32_e32 v194, v194, v195
	ds_bpermute_b32 v195, v59, v194
	s_waitcnt lgkmcnt(0)
	v_add_f32_e32 v194, v194, v195
	s_and_saveexec_b64 s[32:33], s[6:7]
	global_atomic_add_f32 v54, v194, s[70:71] offset:64
	s_or_b64 exec, exec, s[32:33]
	global_load_dword v67, v54, s[68:69] offset:192
	global_load_dwordx4 v[170:173], v56, s[86:87]
	global_load_dwordx4 v[174:177], v56, s[86:87] offset:256
	global_load_dwordx4 v[178:181], v56, s[88:89]
	global_load_dwordx4 v[182:185], v56, s[88:89] offset:256
	s_add_u32 s86, s86, 0xa0000
	s_addc_u32 s87, s87, 0
	s_add_u32 s88, s88, 0xa0000
	s_addc_u32 s89, s89, 0
	s_waitcnt vmcnt(6)
;     __device__ __forceinline__ void operator()(const f32x4 (&acc)[2][2][4][2], const pg8::Unit& u, int wr, int wc, int fr, int fq) const {
;         const int row0 = u.pm * 256 + wr * 64 + fr, col0 = u.pn * 256 + wc * 32 + 8 * fq;
;         f32x4 bv[2][2], sb[2][2];
; #pragma unroll
;         for (int bj = 0; bj < 2; ++bj) { bv[bj][0] = *(const f32x4*)(bg + col0 + bj * 128); bv[bj][1] = *(const f32x4*)(bg + col0 + bj * 128 + 4);
;             sb[bj][0] = *(const f32x4*)(cmax + col0 + bj * 128) * (1.f / 127.f); sb[bj][1] = *(const f32x4*)(cmax + col0 + bj * 128 + 4) * (1.f / 127.f); }
; #pragma unroll
;         for (int ai = 0; ai < 2; ++ai)
; #pragma unroll
;             for (int mp = 0; mp < 2; ++mp) {
;                 u32x4 hr[2][2], pr[2][2]; float q1v[2];
; #pragma unroll
;                 for (int mm = 0; mm < 2; ++mm) { const int row = row0 + ai * 128 + (2 * mp + mm) * 16; q1v[mm] = rss1[row];
; #pragma unroll
;                     for (int bj = 0; bj < 2; ++bj) { const size_t off = (size_t)row * DM + col0 + bj * 128; hr[mm][bj] = *(const u32x4*)(HB + off); pr[mm][bj] = *(const u32x4*)(PP + off); } }
; #pragma unroll
;                 for (int mm = 0; mm < 2; ++mm) { const int m = 2 * mp + mm, row = row0 + ai * 128 + m * 16; f32x4 ssv = {0.f, 0.f, 0.f, 0.f}; const float sa = (QCLIP / 127.f) * sqrtf(q1v[mm] * (1.f / DM) + EPS);
; #pragma unroll
;                     for (int bj = 0; bj < 2; ++bj) { const size_t off = (size_t)row * DM + col0 + bj * 128;
;                         f32x4 p0, p1, x0, x1; unpack8v(pr[mm][bj], p0, p1); unpack8v(hr[mm][bj], x0, x1);
;                         const f32x4 g0 = acc_i2f(acc[ai][bj][m][0]) * (sb[bj][0] * sa) + bv[bj][0], g1 = acc_i2f(acc[ai][bj][m][1]) * (sb[bj][1] * sa) + bv[bj][1];
;                         const f32x4 h0 = x0 + p0 * sigm4(g0), h1 = x1 + p1 * sigm4(g1);
;                         *(f32x4*)(H + off) = h0; *(f32x4*)(H + off + 4) = h1;
;                         ssv = ssv + h0 * h0; ssv = ssv + h1 * h1; }
;                     float ss = (ssv[0] + ssv[1]) + (ssv[2] + ssv[3]);
;                     ss += __shfl_xor(ss, 16); ss += __shfl_xor(ss, 32);
;                     if (fq == 0) unsafeAtomicAdd(rss3 + row, ss); }
;                 asm volatile("" ::: "memory"); }
;     }
	v_fmamk_f32 v186, v66, 0x39800000, v204
	v_mul_f32_e32 v187, 0x4f800000, v186
	v_cmp_gt_f32_e32 vcc, s67, v186
	s_nop 1
	v_cndmask_b32_e32 v186, v186, v187, vcc
	v_sqrt_f32_e32 v190, v186
	s_nop 0
	v_add_u32_e32 v191, -1, v190
	v_add_u32_e32 v192, 1, v190
	v_fma_f32 v193, -v191, v190, v186
	v_fma_f32 v187, -v192, v190, v186
	v_cmp_ge_f32_e64 s[10:11], 0, v193
	s_nop 1
	v_cndmask_b32_e64 v190, v190, v191, s[10:11]
	v_cmp_lt_f32_e64 s[10:11], 0, v187
	s_nop 1
	v_cndmask_b32_e64 v190, v190, v192, s[10:11]
	v_mul_f32_e32 v191, 0x37800000, v190
	v_cndmask_b32_e32 v190, v190, v191, vcc
	v_cmp_class_f32_e32 vcc, v186, v205
	s_nop 1
	v_cndmask_b32_e32 v186, v190, v186, vcc
	v_mul_f32_e32 v188, 0x3d112245, v186
	v_cvt_f32_i32_e32 v110, v110
	v_cvt_f32_i32_e32 v111, v111
	v_cvt_f32_i32_e32 v112, v112
	v_cvt_f32_i32_e32 v113, v113
	v_pk_mul_f32 v[142:143], v[222:223], v[188:189] op_sel_hi:[1,0]
	v_pk_mul_f32 v[144:145], v[224:225], v[188:189] op_sel_hi:[1,0]
	v_pk_fma_f32 v[154:155], v[142:143], v[110:111], v[206:207]
	v_pk_fma_f32 v[156:157], v[144:145], v[112:113], v[208:209]
	v_mul_f32_e32 v154, 0xbfb8aa3b, v154
	v_mul_f32_e32 v155, 0xbfb8aa3b, v155
	v_mul_f32_e32 v156, 0xbfb8aa3b, v156
	v_mul_f32_e32 v157, 0xbfb8aa3b, v157
	v_exp_f32_e32 v154, v154
	v_exp_f32_e32 v155, v155
	v_exp_f32_e32 v156, v156
	v_exp_f32_e32 v157, v157
	v_lshlrev_b32_e32 v146, 16, v238
	v_and_b32_e32 v147, 0xffff0000, v238
	v_lshlrev_b32_e32 v148, 16, v239
	v_and_b32_e32 v149, 0xffff0000, v239
	v_add_f32_e32 v154, 1.0, v154
	v_add_f32_e32 v155, 1.0, v155
	v_add_f32_e32 v156, 1.0, v156
	v_add_f32_e32 v157, 1.0, v157
	v_rcp_f32_e32 v154, v154
	v_rcp_f32_e32 v155, v155
	v_rcp_f32_e32 v156, v156
	v_rcp_f32_e32 v157, v157
	v_lshlrev_b32_e32 v150, 16, v246
	v_and_b32_e32 v151, 0xffff0000, v246
	v_lshlrev_b32_e32 v152, 16, v247
	v_and_b32_e32 v153, 0xffff0000, v247
	v_pk_fma_f32 v[110:111], v[154:155], v[150:151], v[146:147]
	v_pk_fma_f32 v[112:113], v[156:157], v[152:153], v[148:149]
	v_pk_mul_f32 v[194:195], v[110:111], v[110:111]
	v_pk_mul_f32 v[196:197], v[112:113], v[112:113]
	v_cvt_f32_i32_e32 v106, v106
	v_cvt_f32_i32_e32 v107, v107
	v_cvt_f32_i32_e32 v108, v108
	v_cvt_f32_i32_e32 v109, v109
	v_pk_mul_f32 v[142:143], v[226:227], v[188:189] op_sel_hi:[1,0]
	v_pk_mul_f32 v[144:145], v[228:229], v[188:189] op_sel_hi:[1,0]
	v_pk_fma_f32 v[154:155], v[142:143], v[106:107], v[210:211]
	v_pk_fma_f32 v[156:157], v[144:145], v[108:109], v[212:213]
	v_mul_f32_e32 v154, 0xbfb8aa3b, v154
	v_mul_f32_e32 v155, 0xbfb8aa3b, v155
	v_mul_f32_e32 v156, 0xbfb8aa3b, v156
	v_mul_f32_e32 v157, 0xbfb8aa3b, v157
	v_exp_f32_e32 v154, v154
	v_exp_f32_e32 v155, v155
	v_exp_f32_e32 v156, v156
	v_exp_f32_e32 v157, v157
	v_lshlrev_b32_e32 v146, 16, v240
	v_and_b32_e32 v147, 0xffff0000, v240
	v_lshlrev_b32_e32 v148, 16, v241
	v_and_b32_e32 v149, 0xffff0000, v241
	v_add_f32_e32 v154, 1.0, v154
	v_add_f32_e32 v155, 1.0, v155
	v_add_f32_e32 v156, 1.0, v156
	v_add_f32_e32 v157, 1.0, v157
	v_rcp_f32_e32 v154, v154
	v_rcp_f32_e32 v155, v155
	v_rcp_f32_e32 v156, v156
	v_rcp_f32_e32 v157, v157
	v_lshlrev_b32_e32 v150, 16, v248
	v_and_b32_e32 v151, 0xffff0000, v248
	v_lshlrev_b32_e32 v152, 16, v249
	v_and_b32_e32 v153, 0xffff0000, v249
	v_pk_fma_f32 v[106:107], v[154:155], v[150:151], v[146:147]
	v_pk_fma_f32 v[108:109], v[156:157], v[152:153], v[148:149]
	v_pk_fma_f32 v[194:195], v[106:107], v[106:107], v[194:195]
	v_pk_fma_f32 v[196:197], v[108:109], v[108:109], v[196:197]
	v_cvt_f32_i32_e32 v102, v102
	v_cvt_f32_i32_e32 v103, v103
	v_cvt_f32_i32_e32 v104, v104
	v_cvt_f32_i32_e32 v105, v105
	v_pk_mul_f32 v[142:143], v[230:231], v[188:189] op_sel_hi:[1,0]
	v_pk_mul_f32 v[144:145], v[232:233], v[188:189] op_sel_hi:[1,0]
	v_pk_fma_f32 v[154:155], v[142:143], v[102:103], v[214:215]
	v_pk_fma_f32 v[156:157], v[144:145], v[104:105], v[216:217]
	v_mul_f32_e32 v154, 0xbfb8aa3b, v154
	v_mul_f32_e32 v155, 0xbfb8aa3b, v155
	v_mul_f32_e32 v156, 0xbfb8aa3b, v156
	v_mul_f32_e32 v157, 0xbfb8aa3b, v157
	v_exp_f32_e32 v154, v154
	v_exp_f32_e32 v155, v155
	v_exp_f32_e32 v156, v156
	v_exp_f32_e32 v157, v157
	v_lshlrev_b32_e32 v146, 16, v242
	v_and_b32_e32 v147, 0xffff0000, v242
	v_lshlrev_b32_e32 v148, 16, v243
	v_and_b32_e32 v149, 0xffff0000, v243
	v_add_f32_e32 v154, 1.0, v154
	v_add_f32_e32 v155, 1.0, v155
	v_add_f32_e32 v156, 1.0, v156
	v_add_f32_e32 v157, 1.0, v157
	v_rcp_f32_e32 v154, v154
	v_rcp_f32_e32 v155, v155
	v_rcp_f32_e32 v156, v156
	v_rcp_f32_e32 v157, v157
	v_lshlrev_b32_e32 v150, 16, v250
	v_and_b32_e32 v151, 0xffff0000, v250
	v_lshlrev_b32_e32 v152, 16, v251
	v_and_b32_e32 v153, 0xffff0000, v251
	v_pk_fma_f32 v[102:103], v[154:155], v[150:151], v[146:147]
	v_pk_fma_f32 v[104:105], v[156:157], v[152:153], v[148:149]
	v_pk_fma_f32 v[194:195], v[102:103], v[102:103], v[194:195]
	v_pk_fma_f32 v[196:197], v[104:105], v[104:105], v[196:197]
	v_cvt_f32_i32_e32 v98, v98
	v_cvt_f32_i32_e32 v99, v99
	v_cvt_f32_i32_e32 v100, v100
	v_cvt_f32_i32_e32 v101, v101
	v_pk_mul_f32 v[142:143], v[234:235], v[188:189] op_sel_hi:[1,0]
	v_pk_mul_f32 v[144:145], v[236:237], v[188:189] op_sel_hi:[1,0]
	v_pk_fma_f32 v[154:155], v[142:143], v[98:99], v[218:219]
	v_pk_fma_f32 v[156:157], v[144:145], v[100:101], v[220:221]
	v_mul_f32_e32 v154, 0xbfb8aa3b, v154
	v_mul_f32_e32 v155, 0xbfb8aa3b, v155
	v_mul_f32_e32 v156, 0xbfb8aa3b, v156
	v_mul_f32_e32 v157, 0xbfb8aa3b, v157
	v_exp_f32_e32 v154, v154
	v_exp_f32_e32 v155, v155
	v_exp_f32_e32 v156, v156
	v_exp_f32_e32 v157, v157
	v_lshlrev_b32_e32 v146, 16, v244
	v_and_b32_e32 v147, 0xffff0000, v244
	v_lshlrev_b32_e32 v148, 16, v245
	v_and_b32_e32 v149, 0xffff0000, v245
	v_add_f32_e32 v154, 1.0, v154
	v_add_f32_e32 v155, 1.0, v155
	v_add_f32_e32 v156, 1.0, v156
	v_add_f32_e32 v157, 1.0, v157
	v_rcp_f32_e32 v154, v154
	v_rcp_f32_e32 v155, v155
	v_rcp_f32_e32 v156, v156
	v_rcp_f32_e32 v157, v157
	v_lshlrev_b32_e32 v150, 16, v252
	v_and_b32_e32 v151, 0xffff0000, v252
	v_lshlrev_b32_e32 v152, 16, v253
	v_and_b32_e32 v153, 0xffff0000, v253
	v_pk_fma_f32 v[98:99], v[154:155], v[150:151], v[146:147]
	v_pk_fma_f32 v[100:101], v[156:157], v[152:153], v[148:149]
	v_pk_fma_f32 v[194:195], v[98:99], v[98:99], v[194:195]
	v_pk_fma_f32 v[196:197], v[100:101], v[100:101], v[196:197]
	v_add_f32_e32 v194, v194, v195
	v_add_f32_e32 v196, v196, v197
	v_add_f32_e32 v194, v194, v196
	ds_bpermute_b32 v195, v58, v194
	s_waitcnt lgkmcnt(0)
;     __device__ __forceinline__ void operator()(const f32x4 (&acc)[2][2][4][2], const pg8::Unit& u, int wr, int wc, int fr, int fq) const {
;         const int row0 = u.pm * 256 + wr * 64 + fr, col0 = u.pn * 256 + wc * 32 + 8 * fq;
;         f32x4 bv[2][2], sb[2][2];
; #pragma unroll
;         for (int bj = 0; bj < 2; ++bj) { bv[bj][0] = *(const f32x4*)(bg + col0 + bj * 128); bv[bj][1] = *(const f32x4*)(bg + col0 + bj * 128 + 4);
;             sb[bj][0] = *(const f32x4*)(cmax + col0 + bj * 128) * (1.f / 127.f); sb[bj][1] = *(const f32x4*)(cmax + col0 + bj * 128 + 4) * (1.f / 127.f); }
; #pragma unroll
;         for (int ai = 0; ai < 2; ++ai)
; #pragma unroll
;             for (int mp = 0; mp < 2; ++mp) {
;                 u32x4 hr[2][2], pr[2][2]; float q1v[2];
; #pragma unroll
;                 for (int mm = 0; mm < 2; ++mm) { const int row = row0 + ai * 128 + (2 * mp + mm) * 16; q1v[mm] = rss1[row];
; #pragma unroll
;                     for (int bj = 0; bj < 2; ++bj) { const size_t off = (size_t)row * DM + col0 + bj * 128; hr[mm][bj] = *(const u32x4*)(HB + off); pr[mm][bj] = *(const u32x4*)(PP + off); } }
; #pragma unroll
;                 for (int mm = 0; mm < 2; ++mm) { const int m = 2 * mp + mm, row = row0 + ai * 128 + m * 16; f32x4 ssv = {0.f, 0.f, 0.f, 0.f}; const float sa = (QCLIP / 127.f) * sqrtf(q1v[mm] * (1.f / DM) + EPS);
; #pragma unroll
;                     for (int bj = 0; bj < 2; ++bj) { const size_t off = (size_t)row * DM + col0 + bj * 128;
;                         f32x4 p0, p1, x0, x1; unpack8v(pr[mm][bj], p0, p1); unpack8v(hr[mm][bj], x0, x1);
;                         const f32x4 g0 = acc_i2f(acc[ai][bj][m][0]) * (sb[bj][0] * sa) + bv[bj][0], g1 = acc_i2f(acc[ai][bj][m][1]) * (sb[bj][1] * sa) + bv[bj][1];
;                         const f32x4 h0 = x0 + p0 * sigm4(g0), h1 = x1 + p1 * sigm4(g1);
;                         *(f32x4*)(H + off) = h0; *(f32x4*)(H + off + 4) = h1;
;                         ssv = ssv + h0 * h0; ssv = ssv + h1 * h1; }
;                     float ss = (ssv[0] + ssv[1]) + (ssv[2] + ssv[3]);
;                     ss += __shfl_xor(ss, 16); ss += __shfl_xor(ss, 32);
;                     if (fq == 0) unsafeAtomicAdd(rss3 + row, ss); }
;                 asm volatile("" ::: "memory"); }
;     }
	v_add_f32_e32 v194, v194, v195
	ds_bpermute_b32 v195, v59, v194
	s_waitcnt lgkmcnt(0)
	v_add_f32_e32 v194, v194, v195
	s_and_saveexec_b64 s[32:33], s[6:7]
	global_atomic_add_f32 v54, v194, s[70:71] offset:128
	s_or_b64 exec, exec, s[32:33]
	global_load_dword v66, v54, s[68:69] offset:512
	global_load_dwordx4 v[238:241], v56, s[86:87]
	global_load_dwordx4 v[242:245], v56, s[86:87] offset:256
	global_load_dwordx4 v[246:249], v56, s[88:89]
	global_load_dwordx4 v[250:253], v56, s[88:89] offset:256
	s_add_u32 s86, s86, 0x20000
	s_addc_u32 s87, s87, 0
	s_add_u32 s88, s88, 0x20000
	s_addc_u32 s89, s89, 0
	s_waitcnt vmcnt(6)
	v_fmamk_f32 v186, v67, 0x39800000, v204
	v_mul_f32_e32 v187, 0x4f800000, v186
	v_cmp_gt_f32_e32 vcc, s67, v186
	s_nop 1
	v_cndmask_b32_e32 v186, v186, v187, vcc
	v_sqrt_f32_e32 v190, v186
	s_nop 0
	v_add_u32_e32 v191, -1, v190
	v_add_u32_e32 v192, 1, v190
	v_fma_f32 v193, -v191, v190, v186
	v_fma_f32 v187, -v192, v190, v186
	v_cmp_ge_f32_e64 s[10:11], 0, v193
	s_nop 1
	v_cndmask_b32_e64 v190, v190, v191, s[10:11]
	v_cmp_lt_f32_e64 s[10:11], 0, v187
	s_nop 1
	v_cndmask_b32_e64 v190, v190, v192, s[10:11]
	v_mul_f32_e32 v191, 0x37800000, v190
	v_cndmask_b32_e32 v190, v190, v191, vcc
	v_cmp_class_f32_e32 vcc, v186, v205
	s_nop 1
	v_cndmask_b32_e32 v186, v190, v186, vcc
	v_mul_f32_e32 v188, 0x3d112245, v186
	v_cvt_f32_i32_e32 v94, v94
	v_cvt_f32_i32_e32 v95, v95
	v_cvt_f32_i32_e32 v96, v96
	v_cvt_f32_i32_e32 v97, v97
	v_pk_mul_f32 v[142:143], v[222:223], v[188:189] op_sel_hi:[1,0]
	v_pk_mul_f32 v[144:145], v[224:225], v[188:189] op_sel_hi:[1,0]
	v_pk_fma_f32 v[154:155], v[142:143], v[94:95], v[206:207]
	v_pk_fma_f32 v[156:157], v[144:145], v[96:97], v[208:209]
	v_mul_f32_e32 v154, 0xbfb8aa3b, v154
	v_mul_f32_e32 v155, 0xbfb8aa3b, v155
	v_mul_f32_e32 v156, 0xbfb8aa3b, v156
	v_mul_f32_e32 v157, 0xbfb8aa3b, v157
	v_exp_f32_e32 v154, v154
	v_exp_f32_e32 v155, v155
	v_exp_f32_e32 v156, v156
	v_exp_f32_e32 v157, v157
	v_lshlrev_b32_e32 v146, 16, v170
	v_and_b32_e32 v147, 0xffff0000, v170
	v_lshlrev_b32_e32 v148, 16, v171
	v_and_b32_e32 v149, 0xffff0000, v171
	v_add_f32_e32 v154, 1.0, v154
	v_add_f32_e32 v155, 1.0, v155
	v_add_f32_e32 v156, 1.0, v156
	v_add_f32_e32 v157, 1.0, v157
	v_rcp_f32_e32 v154, v154
	v_rcp_f32_e32 v155, v155
	v_rcp_f32_e32 v156, v156
	v_rcp_f32_e32 v157, v157
	v_lshlrev_b32_e32 v150, 16, v178
	v_and_b32_e32 v151, 0xffff0000, v178
	v_lshlrev_b32_e32 v152, 16, v179
	v_and_b32_e32 v153, 0xffff0000, v179
	v_pk_fma_f32 v[94:95], v[154:155], v[150:151], v[146:147]
	v_pk_fma_f32 v[96:97], v[156:157], v[152:153], v[148:149]
	v_pk_mul_f32 v[194:195], v[94:95], v[94:95]
	v_pk_mul_f32 v[196:197], v[96:97], v[96:97]
	v_cvt_f32_i32_e32 v90, v90
	v_cvt_f32_i32_e32 v91, v91
	v_cvt_f32_i32_e32 v92, v92
	v_cvt_f32_i32_e32 v93, v93
	v_pk_mul_f32 v[142:143], v[226:227], v[188:189] op_sel_hi:[1,0]
	v_pk_mul_f32 v[144:145], v[228:229], v[188:189] op_sel_hi:[1,0]
	v_pk_fma_f32 v[154:155], v[142:143], v[90:91], v[210:211]
	v_pk_fma_f32 v[156:157], v[144:145], v[92:93], v[212:213]
	v_mul_f32_e32 v154, 0xbfb8aa3b, v154
	v_mul_f32_e32 v155, 0xbfb8aa3b, v155
	v_mul_f32_e32 v156, 0xbfb8aa3b, v156
	v_mul_f32_e32 v157, 0xbfb8aa3b, v157
	v_exp_f32_e32 v154, v154
	v_exp_f32_e32 v155, v155
	v_exp_f32_e32 v156, v156
	v_exp_f32_e32 v157, v157
	v_lshlrev_b32_e32 v146, 16, v172
	v_and_b32_e32 v147, 0xffff0000, v172
	v_lshlrev_b32_e32 v148, 16, v173
	v_and_b32_e32 v149, 0xffff0000, v173
	v_add_f32_e32 v154, 1.0, v154
	v_add_f32_e32 v155, 1.0, v155
	v_add_f32_e32 v156, 1.0, v156
	v_add_f32_e32 v157, 1.0, v157
	v_rcp_f32_e32 v154, v154
	v_rcp_f32_e32 v155, v155
	v_rcp_f32_e32 v156, v156
	v_rcp_f32_e32 v157, v157
	v_lshlrev_b32_e32 v150, 16, v180
	v_and_b32_e32 v151, 0xffff0000, v180
	v_lshlrev_b32_e32 v152, 16, v181
	v_and_b32_e32 v153, 0xffff0000, v181
	v_pk_fma_f32 v[90:91], v[154:155], v[150:151], v[146:147]
	v_pk_fma_f32 v[92:93], v[156:157], v[152:153], v[148:149]
	v_pk_fma_f32 v[194:195], v[90:91], v[90:91], v[194:195]
	v_pk_fma_f32 v[196:197], v[92:93], v[92:93], v[196:197]
	v_cvt_f32_i32_e32 v86, v86
	v_cvt_f32_i32_e32 v87, v87
	v_cvt_f32_i32_e32 v88, v88
	v_cvt_f32_i32_e32 v89, v89
	v_pk_mul_f32 v[142:143], v[230:231], v[188:189] op_sel_hi:[1,0]
	v_pk_mul_f32 v[144:145], v[232:233], v[188:189] op_sel_hi:[1,0]
	v_pk_fma_f32 v[154:155], v[142:143], v[86:87], v[214:215]
	v_pk_fma_f32 v[156:157], v[144:145], v[88:89], v[216:217]
	v_mul_f32_e32 v154, 0xbfb8aa3b, v154
	v_mul_f32_e32 v155, 0xbfb8aa3b, v155
	v_mul_f32_e32 v156, 0xbfb8aa3b, v156
	v_mul_f32_e32 v157, 0xbfb8aa3b, v157
	v_exp_f32_e32 v154, v154
	v_exp_f32_e32 v155, v155
	v_exp_f32_e32 v156, v156
	v_exp_f32_e32 v157, v157
	v_lshlrev_b32_e32 v146, 16, v174
	v_and_b32_e32 v147, 0xffff0000, v174
	v_lshlrev_b32_e32 v148, 16, v175
	v_and_b32_e32 v149, 0xffff0000, v175
	v_add_f32_e32 v154, 1.0, v154
	v_add_f32_e32 v155, 1.0, v155
	v_add_f32_e32 v156, 1.0, v156
	v_add_f32_e32 v157, 1.0, v157
	v_rcp_f32_e32 v154, v154
	v_rcp_f32_e32 v155, v155
	v_rcp_f32_e32 v156, v156
	v_rcp_f32_e32 v157, v157
	v_lshlrev_b32_e32 v150, 16, v182
	v_and_b32_e32 v151, 0xffff0000, v182
	v_lshlrev_b32_e32 v152, 16, v183
	v_and_b32_e32 v153, 0xffff0000, v183
	v_pk_fma_f32 v[86:87], v[154:155], v[150:151], v[146:147]
	v_pk_fma_f32 v[88:89], v[156:157], v[152:153], v[148:149]
	v_pk_fma_f32 v[194:195], v[86:87], v[86:87], v[194:195]
	v_pk_fma_f32 v[196:197], v[88:89], v[88:89], v[196:197]
	v_cvt_f32_i32_e32 v82, v82
	v_cvt_f32_i32_e32 v83, v83
	v_cvt_f32_i32_e32 v84, v84
	v_cvt_f32_i32_e32 v85, v85
	v_pk_mul_f32 v[142:143], v[234:235], v[188:189] op_sel_hi:[1,0]
	v_pk_mul_f32 v[144:145], v[236:237], v[188:189] op_sel_hi:[1,0]
	v_pk_fma_f32 v[154:155], v[142:143], v[82:83], v[218:219]
	v_pk_fma_f32 v[156:157], v[144:145], v[84:85], v[220:221]
	v_mul_f32_e32 v154, 0xbfb8aa3b, v154
	v_mul_f32_e32 v155, 0xbfb8aa3b, v155
	v_mul_f32_e32 v156, 0xbfb8aa3b, v156
	v_mul_f32_e32 v157, 0xbfb8aa3b, v157
	v_exp_f32_e32 v154, v154
	v_exp_f32_e32 v155, v155
	v_exp_f32_e32 v156, v156
	v_exp_f32_e32 v157, v157
	v_lshlrev_b32_e32 v146, 16, v176
	v_and_b32_e32 v147, 0xffff0000, v176
	v_lshlrev_b32_e32 v148, 16, v177
	v_and_b32_e32 v149, 0xffff0000, v177
	v_add_f32_e32 v154, 1.0, v154
	v_add_f32_e32 v155, 1.0, v155
	v_add_f32_e32 v156, 1.0, v156
	v_add_f32_e32 v157, 1.0, v157
	v_rcp_f32_e32 v154, v154
	v_rcp_f32_e32 v155, v155
	v_rcp_f32_e32 v156, v156
	v_rcp_f32_e32 v157, v157
	v_lshlrev_b32_e32 v150, 16, v184
	v_and_b32_e32 v151, 0xffff0000, v184
	v_lshlrev_b32_e32 v152, 16, v185
	v_and_b32_e32 v153, 0xffff0000, v185
	v_pk_fma_f32 v[82:83], v[154:155], v[150:151], v[146:147]
	v_pk_fma_f32 v[84:85], v[156:157], v[152:153], v[148:149]
	v_pk_fma_f32 v[194:195], v[82:83], v[82:83], v[194:195]
	v_pk_fma_f32 v[196:197], v[84:85], v[84:85], v[196:197]
	v_add_f32_e32 v194, v194, v195
	v_add_f32_e32 v196, v196, v197
	v_add_f32_e32 v194, v194, v196
	ds_bpermute_b32 v195, v58, v194
	s_waitcnt lgkmcnt(0)
;     __device__ __forceinline__ void operator()(const f32x4 (&acc)[2][2][4][2], const pg8::Unit& u, int wr, int wc, int fr, int fq) const {
;         const int row0 = u.pm * 256 + wr * 64 + fr, col0 = u.pn * 256 + wc * 32 + 8 * fq;
;         f32x4 bv[2][2], sb[2][2];
; #pragma unroll
;         for (int bj = 0; bj < 2; ++bj) { bv[bj][0] = *(const f32x4*)(bg + col0 + bj * 128); bv[bj][1] = *(const f32x4*)(bg + col0 + bj * 128 + 4);
;             sb[bj][0] = *(const f32x4*)(cmax + col0 + bj * 128) * (1.f / 127.f); sb[bj][1] = *(const f32x4*)(cmax + col0 + bj * 128 + 4) * (1.f / 127.f); }
; #pragma unroll
;         for (int ai = 0; ai < 2; ++ai)
; #pragma unroll
;             for (int mp = 0; mp < 2; ++mp) {
;                 u32x4 hr[2][2], pr[2][2]; float q1v[2];
; #pragma unroll
;                 for (int mm = 0; mm < 2; ++mm) { const int row = row0 + ai * 128 + (2 * mp + mm) * 16; q1v[mm] = rss1[row];
; #pragma unroll
;                     for (int bj = 0; bj < 2; ++bj) { const size_t off = (size_t)row * DM + col0 + bj * 128; hr[mm][bj] = *(const u32x4*)(HB + off); pr[mm][bj] = *(const u32x4*)(PP + off); } }
; #pragma unroll
;                 for (int mm = 0; mm < 2; ++mm) { const int m = 2 * mp + mm, row = row0 + ai * 128 + m * 16; f32x4 ssv = {0.f, 0.f, 0.f, 0.f}; const float sa = (QCLIP / 127.f) * sqrtf(q1v[mm] * (1.f / DM) + EPS);
; #pragma unroll
;                     for (int bj = 0; bj < 2; ++bj) { const size_t off = (size_t)row * DM + col0 + bj * 128;
;                         f32x4 p0, p1, x0, x1; unpack8v(pr[mm][bj], p0, p1); unpack8v(hr[mm][bj], x0, x1);
;                         const f32x4 g0 = acc_i2f(acc[ai][bj][m][0]) * (sb[bj][0] * sa) + bv[bj][0], g1 = acc_i2f(acc[ai][bj][m][1]) * (sb[bj][1] * sa) + bv[bj][1];
;                         const f32x4 h0 = x0 + p0 * sigm4(g0), h1 = x1 + p1 * sigm4(g1);
;                         *(f32x4*)(H + off) = h0; *(f32x4*)(H + off + 4) = h1;
;                         ssv = ssv + h0 * h0; ssv = ssv + h1 * h1; }
;                     float ss = (ssv[0] + ssv[1]) + (ssv[2] + ssv[3]);
;                     ss += __shfl_xor(ss, 16); ss += __shfl_xor(ss, 32);
;                     if (fq == 0) unsafeAtomicAdd(rss3 + row, ss); }
;                 asm volatile("" ::: "memory"); }
;     }
	v_add_f32_e32 v194, v194, v195
	ds_bpermute_b32 v195, v59, v194
	s_waitcnt lgkmcnt(0)
	v_add_f32_e32 v194, v194, v195
	s_and_saveexec_b64 s[32:33], s[6:7]
	global_atomic_add_f32 v54, v194, s[70:71] offset:192
	s_or_b64 exec, exec, s[32:33]
	global_load_dword v67, v54, s[68:69] offset:576
	global_load_dwordx4 v[170:173], v56, s[86:87]
	global_load_dwordx4 v[174:177], v56, s[86:87] offset:256
	global_load_dwordx4 v[178:181], v56, s[88:89]
	global_load_dwordx4 v[182:185], v56, s[88:89] offset:256
	s_add_u32 s86, s86, 0x20000
	s_addc_u32 s87, s87, 0
	s_add_u32 s88, s88, 0x20000
	s_addc_u32 s89, s89, 0
	s_waitcnt vmcnt(6)
	v_fmamk_f32 v186, v66, 0x39800000, v204
	v_mul_f32_e32 v187, 0x4f800000, v186
	v_cmp_gt_f32_e32 vcc, s67, v186
	s_nop 1
	v_cndmask_b32_e32 v186, v186, v187, vcc
	v_sqrt_f32_e32 v190, v186
	s_nop 0
	v_add_u32_e32 v191, -1, v190
	v_add_u32_e32 v192, 1, v190
	v_fma_f32 v193, -v191, v190, v186
	v_fma_f32 v187, -v192, v190, v186
	v_cmp_ge_f32_e64 s[10:11], 0, v193
	s_nop 1
	v_cndmask_b32_e64 v190, v190, v191, s[10:11]
	v_cmp_lt_f32_e64 s[10:11], 0, v187
	s_nop 1
	v_cndmask_b32_e64 v190, v190, v192, s[10:11]
	v_mul_f32_e32 v191, 0x37800000, v190
	v_cndmask_b32_e32 v190, v190, v191, vcc
	v_cmp_class_f32_e32 vcc, v186, v205
	s_nop 1
	v_cndmask_b32_e32 v186, v190, v186, vcc
	v_mul_f32_e32 v188, 0x3d112245, v186
	v_cvt_f32_i32_e32 v78, v78
	v_cvt_f32_i32_e32 v79, v79
	v_cvt_f32_i32_e32 v80, v80
	v_cvt_f32_i32_e32 v81, v81
	v_pk_mul_f32 v[142:143], v[222:223], v[188:189] op_sel_hi:[1,0]
	v_pk_mul_f32 v[144:145], v[224:225], v[188:189] op_sel_hi:[1,0]
	v_pk_fma_f32 v[154:155], v[142:143], v[78:79], v[206:207]
	v_pk_fma_f32 v[156:157], v[144:145], v[80:81], v[208:209]
	v_mul_f32_e32 v154, 0xbfb8aa3b, v154
	v_mul_f32_e32 v155, 0xbfb8aa3b, v155
	v_mul_f32_e32 v156, 0xbfb8aa3b, v156
	v_mul_f32_e32 v157, 0xbfb8aa3b, v157
	v_exp_f32_e32 v154, v154
	v_exp_f32_e32 v155, v155
	v_exp_f32_e32 v156, v156
	v_exp_f32_e32 v157, v157
	v_lshlrev_b32_e32 v146, 16, v238
	v_and_b32_e32 v147, 0xffff0000, v238
	v_lshlrev_b32_e32 v148, 16, v239
	v_and_b32_e32 v149, 0xffff0000, v239
	v_add_f32_e32 v154, 1.0, v154
	v_add_f32_e32 v155, 1.0, v155
	v_add_f32_e32 v156, 1.0, v156
	v_add_f32_e32 v157, 1.0, v157
	v_rcp_f32_e32 v154, v154
	v_rcp_f32_e32 v155, v155
	v_rcp_f32_e32 v156, v156
	v_rcp_f32_e32 v157, v157
	v_lshlrev_b32_e32 v150, 16, v246
	v_and_b32_e32 v151, 0xffff0000, v246
	v_lshlrev_b32_e32 v152, 16, v247
	v_and_b32_e32 v153, 0xffff0000, v247
	v_pk_fma_f32 v[78:79], v[154:155], v[150:151], v[146:147]
	v_pk_fma_f32 v[80:81], v[156:157], v[152:153], v[148:149]
	v_pk_mul_f32 v[194:195], v[78:79], v[78:79]
	v_pk_mul_f32 v[196:197], v[80:81], v[80:81]
	v_cvt_f32_i32_e32 v74, v74
	v_cvt_f32_i32_e32 v75, v75
	v_cvt_f32_i32_e32 v76, v76
	v_cvt_f32_i32_e32 v77, v77
	v_pk_mul_f32 v[142:143], v[226:227], v[188:189] op_sel_hi:[1,0]
	v_pk_mul_f32 v[144:145], v[228:229], v[188:189] op_sel_hi:[1,0]
	v_pk_fma_f32 v[154:155], v[142:143], v[74:75], v[210:211]
	v_pk_fma_f32 v[156:157], v[144:145], v[76:77], v[212:213]
	v_mul_f32_e32 v154, 0xbfb8aa3b, v154
	v_mul_f32_e32 v155, 0xbfb8aa3b, v155
	v_mul_f32_e32 v156, 0xbfb8aa3b, v156
	v_mul_f32_e32 v157, 0xbfb8aa3b, v157
	v_exp_f32_e32 v154, v154
	v_exp_f32_e32 v155, v155
	v_exp_f32_e32 v156, v156
	v_exp_f32_e32 v157, v157
	v_lshlrev_b32_e32 v146, 16, v240
	v_and_b32_e32 v147, 0xffff0000, v240
	v_lshlrev_b32_e32 v148, 16, v241
	v_and_b32_e32 v149, 0xffff0000, v241
	v_add_f32_e32 v154, 1.0, v154
	v_add_f32_e32 v155, 1.0, v155
	v_add_f32_e32 v156, 1.0, v156
	v_add_f32_e32 v157, 1.0, v157
	v_rcp_f32_e32 v154, v154
	v_rcp_f32_e32 v155, v155
	v_rcp_f32_e32 v156, v156
	v_rcp_f32_e32 v157, v157
	v_lshlrev_b32_e32 v150, 16, v248
	v_and_b32_e32 v151, 0xffff0000, v248
	v_lshlrev_b32_e32 v152, 16, v249
	v_and_b32_e32 v153, 0xffff0000, v249
	v_pk_fma_f32 v[74:75], v[154:155], v[150:151], v[146:147]
	v_pk_fma_f32 v[76:77], v[156:157], v[152:153], v[148:149]
	v_pk_fma_f32 v[194:195], v[74:75], v[74:75], v[194:195]
	v_pk_fma_f32 v[196:197], v[76:77], v[76:77], v[196:197]
	v_cvt_f32_i32_e32 v70, v70
	v_cvt_f32_i32_e32 v71, v71
	v_cvt_f32_i32_e32 v72, v72
	v_cvt_f32_i32_e32 v73, v73
	v_pk_mul_f32 v[142:143], v[230:231], v[188:189] op_sel_hi:[1,0]
	v_pk_mul_f32 v[144:145], v[232:233], v[188:189] op_sel_hi:[1,0]
	v_pk_fma_f32 v[154:155], v[142:143], v[70:71], v[214:215]
	v_pk_fma_f32 v[156:157], v[144:145], v[72:73], v[216:217]
	v_mul_f32_e32 v154, 0xbfb8aa3b, v154
	v_mul_f32_e32 v155, 0xbfb8aa3b, v155
	v_mul_f32_e32 v156, 0xbfb8aa3b, v156
	v_mul_f32_e32 v157, 0xbfb8aa3b, v157
	v_exp_f32_e32 v154, v154
	v_exp_f32_e32 v155, v155
	v_exp_f32_e32 v156, v156
	v_exp_f32_e32 v157, v157
	v_lshlrev_b32_e32 v146, 16, v242
	v_and_b32_e32 v147, 0xffff0000, v242
	v_lshlrev_b32_e32 v148, 16, v243
	v_and_b32_e32 v149, 0xffff0000, v243
	v_add_f32_e32 v154, 1.0, v154
	v_add_f32_e32 v155, 1.0, v155
	v_add_f32_e32 v156, 1.0, v156
	v_add_f32_e32 v157, 1.0, v157
	v_rcp_f32_e32 v154, v154
	v_rcp_f32_e32 v155, v155
	v_rcp_f32_e32 v156, v156
	v_rcp_f32_e32 v157, v157
	v_lshlrev_b32_e32 v150, 16, v250
	v_and_b32_e32 v151, 0xffff0000, v250
	v_lshlrev_b32_e32 v152, 16, v251
	v_and_b32_e32 v153, 0xffff0000, v251
	v_pk_fma_f32 v[70:71], v[154:155], v[150:151], v[146:147]
	v_pk_fma_f32 v[72:73], v[156:157], v[152:153], v[148:149]
	v_pk_fma_f32 v[194:195], v[70:71], v[70:71], v[194:195]
	v_pk_fma_f32 v[196:197], v[72:73], v[72:73], v[196:197]
	v_cvt_f32_i32_e32 v62, v62
	v_cvt_f32_i32_e32 v63, v63
	v_cvt_f32_i32_e32 v64, v64
	v_cvt_f32_i32_e32 v65, v65
	v_pk_mul_f32 v[142:143], v[234:235], v[188:189] op_sel_hi:[1,0]
	v_pk_mul_f32 v[144:145], v[236:237], v[188:189] op_sel_hi:[1,0]
	v_pk_fma_f32 v[154:155], v[142:143], v[62:63], v[218:219]
	v_pk_fma_f32 v[156:157], v[144:145], v[64:65], v[220:221]
	v_mul_f32_e32 v154, 0xbfb8aa3b, v154
	v_mul_f32_e32 v155, 0xbfb8aa3b, v155
	v_mul_f32_e32 v156, 0xbfb8aa3b, v156
	v_mul_f32_e32 v157, 0xbfb8aa3b, v157
	v_exp_f32_e32 v154, v154
	v_exp_f32_e32 v155, v155
	v_exp_f32_e32 v156, v156
	v_exp_f32_e32 v157, v157
	v_lshlrev_b32_e32 v146, 16, v244
	v_and_b32_e32 v147, 0xffff0000, v244
	v_lshlrev_b32_e32 v148, 16, v245
	v_and_b32_e32 v149, 0xffff0000, v245
	v_add_f32_e32 v154, 1.0, v154
	v_add_f32_e32 v155, 1.0, v155
	v_add_f32_e32 v156, 1.0, v156
	v_add_f32_e32 v157, 1.0, v157
	v_rcp_f32_e32 v154, v154
	v_rcp_f32_e32 v155, v155
	v_rcp_f32_e32 v156, v156
	v_rcp_f32_e32 v157, v157
	v_lshlrev_b32_e32 v150, 16, v252
	v_and_b32_e32 v151, 0xffff0000, v252
	v_lshlrev_b32_e32 v152, 16, v253
	v_and_b32_e32 v153, 0xffff0000, v253
	v_pk_fma_f32 v[62:63], v[154:155], v[150:151], v[146:147]
	v_pk_fma_f32 v[64:65], v[156:157], v[152:153], v[148:149]
	v_pk_fma_f32 v[194:195], v[62:63], v[62:63], v[194:195]
	v_pk_fma_f32 v[196:197], v[64:65], v[64:65], v[196:197]
	v_add_f32_e32 v194, v194, v195
	v_add_f32_e32 v196, v196, v197
	v_add_f32_e32 v194, v194, v196
	ds_bpermute_b32 v195, v58, v194
	s_waitcnt lgkmcnt(0)
; __device__ __forceinline__ f32x4 acc_i2f(const f32x4 a) { return __builtin_convertvector(__builtin_bit_cast(i32x4, a), f32x4); }
;     __device__ __forceinline__ void operator()(const f32x4 (&acc)[2][2][4][2], const pg8::Unit& u, int wr, int wc, int fr, int fq) const {
;     ...
;                 u32x4 hr[2][2], pr[2][2]; float q1v[2];
; #pragma unroll
;                 for (int mm = 0; mm < 2; ++mm) { const int row = row0 + ai * 128 + (2 * mp + mm) * 16; q1v[mm] = rss1[row];
; #pragma unroll
;                     for (int bj = 0; bj < 2; ++bj) { const size_t off = (size_t)row * DM + col0 + bj * 128; hr[mm][bj] = *(const u32x4*)(HB + off); pr[mm][bj] = *(const u32x4*)(PP + off); } }
; #pragma unroll
;                 for (int mm = 0; mm < 2; ++mm) { const int m = 2 * mp + mm, row = row0 + ai * 128 + m * 16; f32x4 ssv = {0.f, 0.f, 0.f, 0.f}; const float sa = (QCLIP / 127.f) * sqrtf(q1v[mm] * (1.f / DM) + EPS);
; #pragma unroll
;                     for (int bj = 0; bj < 2; ++bj) { const size_t off = (size_t)row * DM + col0 + bj * 128;
;                         f32x4 p0, p1, x0, x1; unpack8v(pr[mm][bj], p0, p1); unpack8v(hr[mm][bj], x0, x1);
;                         const f32x4 g0 = acc_i2f(acc[ai][bj][m][0]) * (sb[bj][0] * sa) + bv[bj][0], g1 = acc_i2f(acc[ai][bj][m][1]) * (sb[bj][1] * sa) + bv[bj][1];
;                         const f32x4 h0 = x0 + p0 * sigm4(g0), h1 = x1 + p1 * sigm4(g1);
;                         *(f32x4*)(H + off) = h0; *(f32x4*)(H + off + 4) = h1;
;                         ssv = ssv + h0 * h0; ssv = ssv + h1 * h1; }
;                     float ss = (ssv[0] + ssv[1]) + (ssv[2] + ssv[3]);
;                     ss += __shfl_xor(ss, 16); ss += __shfl_xor(ss, 32);
;                     if (fq == 0) unsafeAtomicAdd(rss3 + row, ss); }
	v_add_f32_e32 v194, v194, v195
	ds_bpermute_b32 v195, v59, v194
	s_waitcnt lgkmcnt(0)
	v_add_f32_e32 v194, v194, v195
	s_and_saveexec_b64 s[32:33], s[6:7]
	global_atomic_add_f32 v54, v194, s[70:71] offset:512
	s_or_b64 exec, exec, s[32:33]
	global_load_dword v66, v54, s[68:69] offset:640
	global_load_dwordx4 v[238:241], v56, s[86:87]
	global_load_dwordx4 v[242:245], v56, s[86:87] offset:256
	global_load_dwordx4 v[246:249], v56, s[88:89]
	global_load_dwordx4 v[250:253], v56, s[88:89] offset:256
	s_add_u32 s86, s86, 0x20000
	s_addc_u32 s87, s87, 0
	s_add_u32 s88, s88, 0x20000
	s_addc_u32 s89, s89, 0
	s_waitcnt vmcnt(6)
	v_fmamk_f32 v186, v67, 0x39800000, v204
	v_mul_f32_e32 v187, 0x4f800000, v186
	v_cmp_gt_f32_e32 vcc, s67, v186
	s_nop 1
	v_cndmask_b32_e32 v186, v186, v187, vcc
	v_sqrt_f32_e32 v190, v186
	s_nop 0
	v_add_u32_e32 v191, -1, v190
	v_add_u32_e32 v192, 1, v190
	v_fma_f32 v193, -v191, v190, v186
	v_fma_f32 v187, -v192, v190, v186
	v_cmp_ge_f32_e64 s[10:11], 0, v193
	s_nop 1
	v_cndmask_b32_e64 v190, v190, v191, s[10:11]
	v_cmp_lt_f32_e64 s[10:11], 0, v187
	s_nop 1
	v_cndmask_b32_e64 v190, v190, v192, s[10:11]
	v_mul_f32_e32 v191, 0x37800000, v190
	v_cndmask_b32_e32 v190, v190, v191, vcc
	v_cmp_class_f32_e32 vcc, v186, v205
	s_nop 1
	v_cndmask_b32_e32 v186, v190, v186, vcc
	v_mul_f32_e32 v188, 0x3d112245, v186
	v_cvt_f32_i32_e32 v46, v46
	v_cvt_f32_i32_e32 v47, v47
	v_cvt_f32_i32_e32 v48, v48
	v_cvt_f32_i32_e32 v49, v49
	v_pk_mul_f32 v[142:143], v[222:223], v[188:189] op_sel_hi:[1,0]
	v_pk_mul_f32 v[144:145], v[224:225], v[188:189] op_sel_hi:[1,0]
	v_pk_fma_f32 v[154:155], v[142:143], v[46:47], v[206:207]
	v_pk_fma_f32 v[156:157], v[144:145], v[48:49], v[208:209]
	v_mul_f32_e32 v154, 0xbfb8aa3b, v154
	v_mul_f32_e32 v155, 0xbfb8aa3b, v155
	v_mul_f32_e32 v156, 0xbfb8aa3b, v156
	v_mul_f32_e32 v157, 0xbfb8aa3b, v157
	v_exp_f32_e32 v154, v154
	v_exp_f32_e32 v155, v155
	v_exp_f32_e32 v156, v156
	v_exp_f32_e32 v157, v157
	v_lshlrev_b32_e32 v146, 16, v170
	v_and_b32_e32 v147, 0xffff0000, v170
	v_lshlrev_b32_e32 v148, 16, v171
	v_and_b32_e32 v149, 0xffff0000, v171
	v_add_f32_e32 v154, 1.0, v154
	v_add_f32_e32 v155, 1.0, v155
	v_add_f32_e32 v156, 1.0, v156
	v_add_f32_e32 v157, 1.0, v157
	v_rcp_f32_e32 v154, v154
	v_rcp_f32_e32 v155, v155
	v_rcp_f32_e32 v156, v156
	v_rcp_f32_e32 v157, v157
	v_lshlrev_b32_e32 v150, 16, v178
	v_and_b32_e32 v151, 0xffff0000, v178
	v_lshlrev_b32_e32 v152, 16, v179
	v_and_b32_e32 v153, 0xffff0000, v179
	v_pk_fma_f32 v[46:47], v[154:155], v[150:151], v[146:147]
	v_pk_fma_f32 v[48:49], v[156:157], v[152:153], v[148:149]
	v_pk_mul_f32 v[194:195], v[46:47], v[46:47]
	v_pk_mul_f32 v[196:197], v[48:49], v[48:49]
	v_cvt_f32_i32_e32 v42, v42
	v_cvt_f32_i32_e32 v43, v43
	v_cvt_f32_i32_e32 v44, v44
	v_cvt_f32_i32_e32 v45, v45
	v_pk_mul_f32 v[142:143], v[226:227], v[188:189] op_sel_hi:[1,0]
	v_pk_mul_f32 v[144:145], v[228:229], v[188:189] op_sel_hi:[1,0]
	v_pk_fma_f32 v[154:155], v[142:143], v[42:43], v[210:211]
	v_pk_fma_f32 v[156:157], v[144:145], v[44:45], v[212:213]
	v_mul_f32_e32 v154, 0xbfb8aa3b, v154
	v_mul_f32_e32 v155, 0xbfb8aa3b, v155
	v_mul_f32_e32 v156, 0xbfb8aa3b, v156
	v_mul_f32_e32 v157, 0xbfb8aa3b, v157
	v_exp_f32_e32 v154, v154
	v_exp_f32_e32 v155, v155
	v_exp_f32_e32 v156, v156
	v_exp_f32_e32 v157, v157
	v_lshlrev_b32_e32 v146, 16, v172
	v_and_b32_e32 v147, 0xffff0000, v172
	v_lshlrev_b32_e32 v148, 16, v173
	v_and_b32_e32 v149, 0xffff0000, v173
	v_add_f32_e32 v154, 1.0, v154
	v_add_f32_e32 v155, 1.0, v155
	v_add_f32_e32 v156, 1.0, v156
	v_add_f32_e32 v157, 1.0, v157
	v_rcp_f32_e32 v154, v154
	v_rcp_f32_e32 v155, v155
	v_rcp_f32_e32 v156, v156
	v_rcp_f32_e32 v157, v157
	v_lshlrev_b32_e32 v150, 16, v180
	v_and_b32_e32 v151, 0xffff0000, v180
	v_lshlrev_b32_e32 v152, 16, v181
	v_and_b32_e32 v153, 0xffff0000, v181
	v_pk_fma_f32 v[42:43], v[154:155], v[150:151], v[146:147]
	v_pk_fma_f32 v[44:45], v[156:157], v[152:153], v[148:149]
	v_pk_fma_f32 v[194:195], v[42:43], v[42:43], v[194:195]
	v_pk_fma_f32 v[196:197], v[44:45], v[44:45], v[196:197]
	v_cvt_f32_i32_e32 v38, v38
	v_cvt_f32_i32_e32 v39, v39
	v_cvt_f32_i32_e32 v40, v40
	v_cvt_f32_i32_e32 v41, v41
	v_pk_mul_f32 v[142:143], v[230:231], v[188:189] op_sel_hi:[1,0]
	v_pk_mul_f32 v[144:145], v[232:233], v[188:189] op_sel_hi:[1,0]
	v_pk_fma_f32 v[154:155], v[142:143], v[38:39], v[214:215]
	v_pk_fma_f32 v[156:157], v[144:145], v[40:41], v[216:217]
	v_mul_f32_e32 v154, 0xbfb8aa3b, v154
	v_mul_f32_e32 v155, 0xbfb8aa3b, v155
	v_mul_f32_e32 v156, 0xbfb8aa3b, v156
	v_mul_f32_e32 v157, 0xbfb8aa3b, v157
	v_exp_f32_e32 v154, v154
	v_exp_f32_e32 v155, v155
	v_exp_f32_e32 v156, v156
	v_exp_f32_e32 v157, v157
	v_lshlrev_b32_e32 v146, 16, v174
	v_and_b32_e32 v147, 0xffff0000, v174
	v_lshlrev_b32_e32 v148, 16, v175
	v_and_b32_e32 v149, 0xffff0000, v175
	v_add_f32_e32 v154, 1.0, v154
	v_add_f32_e32 v155, 1.0, v155
	v_add_f32_e32 v156, 1.0, v156
	v_add_f32_e32 v157, 1.0, v157
	v_rcp_f32_e32 v154, v154
	v_rcp_f32_e32 v155, v155
	v_rcp_f32_e32 v156, v156
	v_rcp_f32_e32 v157, v157
	v_lshlrev_b32_e32 v150, 16, v182
	v_and_b32_e32 v151, 0xffff0000, v182
	v_lshlrev_b32_e32 v152, 16, v183
	v_and_b32_e32 v153, 0xffff0000, v183
	v_pk_fma_f32 v[38:39], v[154:155], v[150:151], v[146:147]
	v_pk_fma_f32 v[40:41], v[156:157], v[152:153], v[148:149]
	v_pk_fma_f32 v[194:195], v[38:39], v[38:39], v[194:195]
	v_pk_fma_f32 v[196:197], v[40:41], v[40:41], v[196:197]
	v_cvt_f32_i32_e32 v34, v34
	v_cvt_f32_i32_e32 v35, v35
	v_cvt_f32_i32_e32 v36, v36
	v_cvt_f32_i32_e32 v37, v37
	v_pk_mul_f32 v[142:143], v[234:235], v[188:189] op_sel_hi:[1,0]
	v_pk_mul_f32 v[144:145], v[236:237], v[188:189] op_sel_hi:[1,0]
	v_pk_fma_f32 v[154:155], v[142:143], v[34:35], v[218:219]
	v_pk_fma_f32 v[156:157], v[144:145], v[36:37], v[220:221]
	v_mul_f32_e32 v154, 0xbfb8aa3b, v154
	v_mul_f32_e32 v155, 0xbfb8aa3b, v155
	v_mul_f32_e32 v156, 0xbfb8aa3b, v156
	v_mul_f32_e32 v157, 0xbfb8aa3b, v157
	v_exp_f32_e32 v154, v154
	v_exp_f32_e32 v155, v155
	v_exp_f32_e32 v156, v156
	v_exp_f32_e32 v157, v157
	v_lshlrev_b32_e32 v146, 16, v176
	v_and_b32_e32 v147, 0xffff0000, v176
	v_lshlrev_b32_e32 v148, 16, v177
	v_and_b32_e32 v149, 0xffff0000, v177
	v_add_f32_e32 v154, 1.0, v154
	v_add_f32_e32 v155, 1.0, v155
	v_add_f32_e32 v156, 1.0, v156
	v_add_f32_e32 v157, 1.0, v157
	v_rcp_f32_e32 v154, v154
	v_rcp_f32_e32 v155, v155
	v_rcp_f32_e32 v156, v156
	v_rcp_f32_e32 v157, v157
	v_lshlrev_b32_e32 v150, 16, v184
	v_and_b32_e32 v151, 0xffff0000, v184
	v_lshlrev_b32_e32 v152, 16, v185
	v_and_b32_e32 v153, 0xffff0000, v185
	v_pk_fma_f32 v[34:35], v[154:155], v[150:151], v[146:147]
	v_pk_fma_f32 v[36:37], v[156:157], v[152:153], v[148:149]
	v_pk_fma_f32 v[194:195], v[34:35], v[34:35], v[194:195]
	v_pk_fma_f32 v[196:197], v[36:37], v[36:37], v[196:197]
	v_add_f32_e32 v194, v194, v195
	v_add_f32_e32 v196, v196, v197
	v_add_f32_e32 v194, v194, v196
	ds_bpermute_b32 v195, v58, v194
	s_waitcnt lgkmcnt(0)
; __device__ __forceinline__ f32x4 acc_i2f(const f32x4 a) { return __builtin_convertvector(__builtin_bit_cast(i32x4, a), f32x4); }
;     __device__ __forceinline__ void operator()(const f32x4 (&acc)[2][2][4][2], const pg8::Unit& u, int wr, int wc, int fr, int fq) const {
;     ...
;                 u32x4 hr[2][2], pr[2][2]; float q1v[2];
; #pragma unroll
;                 for (int mm = 0; mm < 2; ++mm) { const int row = row0 + ai * 128 + (2 * mp + mm) * 16; q1v[mm] = rss1[row];
; #pragma unroll
;                     for (int bj = 0; bj < 2; ++bj) { const size_t off = (size_t)row * DM + col0 + bj * 128; hr[mm][bj] = *(const u32x4*)(HB + off); pr[mm][bj] = *(const u32x4*)(PP + off); } }
; #pragma unroll
;                 for (int mm = 0; mm < 2; ++mm) { const int m = 2 * mp + mm, row = row0 + ai * 128 + m * 16; f32x4 ssv = {0.f, 0.f, 0.f, 0.f}; const float sa = (QCLIP / 127.f) * sqrtf(q1v[mm] * (1.f / DM) + EPS);
; #pragma unroll
;                     for (int bj = 0; bj < 2; ++bj) { const size_t off = (size_t)row * DM + col0 + bj * 128;
;                         f32x4 p0, p1, x0, x1; unpack8v(pr[mm][bj], p0, p1); unpack8v(hr[mm][bj], x0, x1);
;                         const f32x4 g0 = acc_i2f(acc[ai][bj][m][0]) * (sb[bj][0] * sa) + bv[bj][0], g1 = acc_i2f(acc[ai][bj][m][1]) * (sb[bj][1] * sa) + bv[bj][1];
;                         const f32x4 h0 = x0 + p0 * sigm4(g0), h1 = x1 + p1 * sigm4(g1);
;                         *(f32x4*)(H + off) = h0; *(f32x4*)(H + off + 4) = h1;
;                         ssv = ssv + h0 * h0; ssv = ssv + h1 * h1; }
;                     float ss = (ssv[0] + ssv[1]) + (ssv[2] + ssv[3]);
;                     ss += __shfl_xor(ss, 16); ss += __shfl_xor(ss, 32);
;                     if (fq == 0) unsafeAtomicAdd(rss3 + row, ss); }
	v_add_f32_e32 v194, v194, v195
	ds_bpermute_b32 v195, v59, v194
	s_waitcnt lgkmcnt(0)
	v_add_f32_e32 v194, v194, v195
	s_and_saveexec_b64 s[32:33], s[6:7]
	global_atomic_add_f32 v54, v194, s[70:71] offset:576
	s_or_b64 exec, exec, s[32:33]
	global_load_dword v67, v54, s[68:69] offset:704
	global_load_dwordx4 v[170:173], v56, s[86:87]
	global_load_dwordx4 v[174:177], v56, s[86:87] offset:256
	global_load_dwordx4 v[178:181], v56, s[88:89]
	global_load_dwordx4 v[182:185], v56, s[88:89] offset:256
	s_waitcnt vmcnt(6)
	v_fmamk_f32 v186, v66, 0x39800000, v204
	v_mul_f32_e32 v187, 0x4f800000, v186
	v_cmp_gt_f32_e32 vcc, s67, v186
	s_nop 1
	v_cndmask_b32_e32 v186, v186, v187, vcc
	v_sqrt_f32_e32 v190, v186
	s_nop 0
	v_add_u32_e32 v191, -1, v190
	v_add_u32_e32 v192, 1, v190
	v_fma_f32 v193, -v191, v190, v186
	v_fma_f32 v187, -v192, v190, v186
	v_cmp_ge_f32_e64 s[10:11], 0, v193
	s_nop 1
	v_cndmask_b32_e64 v190, v190, v191, s[10:11]
	v_cmp_lt_f32_e64 s[10:11], 0, v187
	s_nop 1
	v_cndmask_b32_e64 v190, v190, v192, s[10:11]
	v_mul_f32_e32 v191, 0x37800000, v190
	v_cndmask_b32_e32 v190, v190, v191, vcc
	v_cmp_class_f32_e32 vcc, v186, v205
	s_nop 1
	v_cndmask_b32_e32 v186, v190, v186, vcc
	v_mul_f32_e32 v188, 0x3d112245, v186
	v_cvt_f32_i32_e32 v30, v30
	v_cvt_f32_i32_e32 v31, v31
	v_cvt_f32_i32_e32 v32, v32
	v_cvt_f32_i32_e32 v33, v33
	v_pk_mul_f32 v[142:143], v[222:223], v[188:189] op_sel_hi:[1,0]
	v_pk_mul_f32 v[144:145], v[224:225], v[188:189] op_sel_hi:[1,0]
	v_pk_fma_f32 v[154:155], v[142:143], v[30:31], v[206:207]
	v_pk_fma_f32 v[156:157], v[144:145], v[32:33], v[208:209]
	v_mul_f32_e32 v154, 0xbfb8aa3b, v154
	v_mul_f32_e32 v155, 0xbfb8aa3b, v155
	v_mul_f32_e32 v156, 0xbfb8aa3b, v156
	v_mul_f32_e32 v157, 0xbfb8aa3b, v157
	v_exp_f32_e32 v154, v154
	v_exp_f32_e32 v155, v155
	v_exp_f32_e32 v156, v156
	v_exp_f32_e32 v157, v157
	v_lshlrev_b32_e32 v146, 16, v238
	v_and_b32_e32 v147, 0xffff0000, v238
	v_lshlrev_b32_e32 v148, 16, v239
	v_and_b32_e32 v149, 0xffff0000, v239
	v_add_f32_e32 v154, 1.0, v154
	v_add_f32_e32 v155, 1.0, v155
	v_add_f32_e32 v156, 1.0, v156
	v_add_f32_e32 v157, 1.0, v157
	v_rcp_f32_e32 v154, v154
	v_rcp_f32_e32 v155, v155
	v_rcp_f32_e32 v156, v156
	v_rcp_f32_e32 v157, v157
	v_lshlrev_b32_e32 v150, 16, v246
	v_and_b32_e32 v151, 0xffff0000, v246
	v_lshlrev_b32_e32 v152, 16, v247
	v_and_b32_e32 v153, 0xffff0000, v247
	v_pk_fma_f32 v[30:31], v[154:155], v[150:151], v[146:147]
	v_pk_fma_f32 v[32:33], v[156:157], v[152:153], v[148:149]
	v_pk_mul_f32 v[194:195], v[30:31], v[30:31]
	v_pk_mul_f32 v[196:197], v[32:33], v[32:33]
	v_cvt_f32_i32_e32 v26, v26
	v_cvt_f32_i32_e32 v27, v27
	v_cvt_f32_i32_e32 v28, v28
	v_cvt_f32_i32_e32 v29, v29
	v_pk_mul_f32 v[142:143], v[226:227], v[188:189] op_sel_hi:[1,0]
	v_pk_mul_f32 v[144:145], v[228:229], v[188:189] op_sel_hi:[1,0]
	v_pk_fma_f32 v[154:155], v[142:143], v[26:27], v[210:211]
	v_pk_fma_f32 v[156:157], v[144:145], v[28:29], v[212:213]
	v_mul_f32_e32 v154, 0xbfb8aa3b, v154
	v_mul_f32_e32 v155, 0xbfb8aa3b, v155
	v_mul_f32_e32 v156, 0xbfb8aa3b, v156
	v_mul_f32_e32 v157, 0xbfb8aa3b, v157
	v_exp_f32_e32 v154, v154
	v_exp_f32_e32 v155, v155
	v_exp_f32_e32 v156, v156
	v_exp_f32_e32 v157, v157
	v_lshlrev_b32_e32 v146, 16, v240
	v_and_b32_e32 v147, 0xffff0000, v240
	v_lshlrev_b32_e32 v148, 16, v241
	v_and_b32_e32 v149, 0xffff0000, v241
	v_add_f32_e32 v154, 1.0, v154
	v_add_f32_e32 v155, 1.0, v155
	v_add_f32_e32 v156, 1.0, v156
	v_add_f32_e32 v157, 1.0, v157
	v_rcp_f32_e32 v154, v154
	v_rcp_f32_e32 v155, v155
	v_rcp_f32_e32 v156, v156
	v_rcp_f32_e32 v157, v157
	v_lshlrev_b32_e32 v150, 16, v248
	v_and_b32_e32 v151, 0xffff0000, v248
	v_lshlrev_b32_e32 v152, 16, v249
	v_and_b32_e32 v153, 0xffff0000, v249
	v_pk_fma_f32 v[26:27], v[154:155], v[150:151], v[146:147]
	v_pk_fma_f32 v[28:29], v[156:157], v[152:153], v[148:149]
	v_pk_fma_f32 v[194:195], v[26:27], v[26:27], v[194:195]
	v_pk_fma_f32 v[196:197], v[28:29], v[28:29], v[196:197]
	v_cvt_f32_i32_e32 v22, v22
	v_cvt_f32_i32_e32 v23, v23
	v_cvt_f32_i32_e32 v24, v24
	v_cvt_f32_i32_e32 v25, v25
	v_pk_mul_f32 v[142:143], v[230:231], v[188:189] op_sel_hi:[1,0]
	v_pk_mul_f32 v[144:145], v[232:233], v[188:189] op_sel_hi:[1,0]
	v_pk_fma_f32 v[154:155], v[142:143], v[22:23], v[214:215]
	v_pk_fma_f32 v[156:157], v[144:145], v[24:25], v[216:217]
	v_mul_f32_e32 v154, 0xbfb8aa3b, v154
	v_mul_f32_e32 v155, 0xbfb8aa3b, v155
	v_mul_f32_e32 v156, 0xbfb8aa3b, v156
	v_mul_f32_e32 v157, 0xbfb8aa3b, v157
	v_exp_f32_e32 v154, v154
	v_exp_f32_e32 v155, v155
	v_exp_f32_e32 v156, v156
	v_exp_f32_e32 v157, v157
	v_lshlrev_b32_e32 v146, 16, v242
	v_and_b32_e32 v147, 0xffff0000, v242
	v_lshlrev_b32_e32 v148, 16, v243
	v_and_b32_e32 v149, 0xffff0000, v243
	v_add_f32_e32 v154, 1.0, v154
	v_add_f32_e32 v155, 1.0, v155
	v_add_f32_e32 v156, 1.0, v156
	v_add_f32_e32 v157, 1.0, v157
	v_rcp_f32_e32 v154, v154
	v_rcp_f32_e32 v155, v155
	v_rcp_f32_e32 v156, v156
	v_rcp_f32_e32 v157, v157
	v_lshlrev_b32_e32 v150, 16, v250
	v_and_b32_e32 v151, 0xffff0000, v250
	v_lshlrev_b32_e32 v152, 16, v251
	v_and_b32_e32 v153, 0xffff0000, v251
	v_pk_fma_f32 v[22:23], v[154:155], v[150:151], v[146:147]
	v_pk_fma_f32 v[24:25], v[156:157], v[152:153], v[148:149]
	v_pk_fma_f32 v[194:195], v[22:23], v[22:23], v[194:195]
	v_pk_fma_f32 v[196:197], v[24:25], v[24:25], v[196:197]
	v_cvt_f32_i32_e32 v18, v18
	v_cvt_f32_i32_e32 v19, v19
	v_cvt_f32_i32_e32 v20, v20
	v_cvt_f32_i32_e32 v21, v21
	v_pk_mul_f32 v[142:143], v[234:235], v[188:189] op_sel_hi:[1,0]
	v_pk_mul_f32 v[144:145], v[236:237], v[188:189] op_sel_hi:[1,0]
	v_pk_fma_f32 v[154:155], v[142:143], v[18:19], v[218:219]
	v_pk_fma_f32 v[156:157], v[144:145], v[20:21], v[220:221]
	v_mul_f32_e32 v154, 0xbfb8aa3b, v154
	v_mul_f32_e32 v155, 0xbfb8aa3b, v155
	v_mul_f32_e32 v156, 0xbfb8aa3b, v156
	v_mul_f32_e32 v157, 0xbfb8aa3b, v157
	v_exp_f32_e32 v154, v154
	v_exp_f32_e32 v155, v155
	v_exp_f32_e32 v156, v156
	v_exp_f32_e32 v157, v157
	v_lshlrev_b32_e32 v146, 16, v244
	v_and_b32_e32 v147, 0xffff0000, v244
	v_lshlrev_b32_e32 v148, 16, v245
	v_and_b32_e32 v149, 0xffff0000, v245
	v_add_f32_e32 v154, 1.0, v154
	v_add_f32_e32 v155, 1.0, v155
	v_add_f32_e32 v156, 1.0, v156
	v_add_f32_e32 v157, 1.0, v157
	v_rcp_f32_e32 v154, v154
	v_rcp_f32_e32 v155, v155
	v_rcp_f32_e32 v156, v156
	v_rcp_f32_e32 v157, v157
	v_lshlrev_b32_e32 v150, 16, v252
	v_and_b32_e32 v151, 0xffff0000, v252
	v_lshlrev_b32_e32 v152, 16, v253
	v_and_b32_e32 v153, 0xffff0000, v253
	v_pk_fma_f32 v[18:19], v[154:155], v[150:151], v[146:147]
	v_pk_fma_f32 v[20:21], v[156:157], v[152:153], v[148:149]
	v_pk_fma_f32 v[194:195], v[18:19], v[18:19], v[194:195]
	v_pk_fma_f32 v[196:197], v[20:21], v[20:21], v[196:197]
	v_add_f32_e32 v194, v194, v195
	v_add_f32_e32 v196, v196, v197
	v_add_f32_e32 v194, v194, v196
	ds_bpermute_b32 v195, v58, v194
	s_waitcnt lgkmcnt(0)
; __device__ __forceinline__ f32x4 acc_i2f(const f32x4 a) { return __builtin_convertvector(__builtin_bit_cast(i32x4, a), f32x4); }
;     __device__ __forceinline__ void operator()(const f32x4 (&acc)[2][2][4][2], const pg8::Unit& u, int wr, int wc, int fr, int fq) const {
;     ...
;                 u32x4 hr[2][2], pr[2][2]; float q1v[2];
; #pragma unroll
;                 for (int mm = 0; mm < 2; ++mm) { const int row = row0 + ai * 128 + (2 * mp + mm) * 16; q1v[mm] = rss1[row];
; #pragma unroll
;                     for (int bj = 0; bj < 2; ++bj) { const size_t off = (size_t)row * DM + col0 + bj * 128; hr[mm][bj] = *(const u32x4*)(HB + off); pr[mm][bj] = *(const u32x4*)(PP + off); } }
; #pragma unroll
;                 for (int mm = 0; mm < 2; ++mm) { const int m = 2 * mp + mm, row = row0 + ai * 128 + m * 16; f32x4 ssv = {0.f, 0.f, 0.f, 0.f}; const float sa = (QCLIP / 127.f) * sqrtf(q1v[mm] * (1.f / DM) + EPS);
; #pragma unroll
;                     for (int bj = 0; bj < 2; ++bj) { const size_t off = (size_t)row * DM + col0 + bj * 128;
;                         f32x4 p0, p1, x0, x1; unpack8v(pr[mm][bj], p0, p1); unpack8v(hr[mm][bj], x0, x1);
;                         const f32x4 g0 = acc_i2f(acc[ai][bj][m][0]) * (sb[bj][0] * sa) + bv[bj][0], g1 = acc_i2f(acc[ai][bj][m][1]) * (sb[bj][1] * sa) + bv[bj][1];
;                         const f32x4 h0 = x0 + p0 * sigm4(g0), h1 = x1 + p1 * sigm4(g1);
;                         *(f32x4*)(H + off) = h0; *(f32x4*)(H + off + 4) = h1;
;                         ssv = ssv + h0 * h0; ssv = ssv + h1 * h1; }
;                     float ss = (ssv[0] + ssv[1]) + (ssv[2] + ssv[3]);
;                     ss += __shfl_xor(ss, 16); ss += __shfl_xor(ss, 32);
;                     if (fq == 0) unsafeAtomicAdd(rss3 + row, ss); }
	v_add_f32_e32 v194, v194, v195
	ds_bpermute_b32 v195, v59, v194
	s_waitcnt lgkmcnt(0)
	v_add_f32_e32 v194, v194, v195
	s_and_saveexec_b64 s[32:33], s[6:7]
	global_atomic_add_f32 v54, v194, s[70:71] offset:640
	s_or_b64 exec, exec, s[32:33]
	s_waitcnt vmcnt(1)
	v_fmamk_f32 v186, v67, 0x39800000, v204
	v_mul_f32_e32 v187, 0x4f800000, v186
	v_cmp_gt_f32_e32 vcc, s67, v186
	s_nop 1
	v_cndmask_b32_e32 v186, v186, v187, vcc
	v_sqrt_f32_e32 v190, v186
	s_nop 0
	v_add_u32_e32 v191, -1, v190
	v_add_u32_e32 v192, 1, v190
	v_fma_f32 v193, -v191, v190, v186
	v_fma_f32 v187, -v192, v190, v186
	v_cmp_ge_f32_e64 s[10:11], 0, v193
	s_nop 1
	v_cndmask_b32_e64 v190, v190, v191, s[10:11]
	v_cmp_lt_f32_e64 s[10:11], 0, v187
	s_nop 1
	v_cndmask_b32_e64 v190, v190, v192, s[10:11]
	v_mul_f32_e32 v191, 0x37800000, v190
	v_cndmask_b32_e32 v190, v190, v191, vcc
	v_cmp_class_f32_e32 vcc, v186, v205
	s_nop 1
	v_cndmask_b32_e32 v186, v190, v186, vcc
	v_mul_f32_e32 v188, 0x3d112245, v186
	v_cvt_f32_i32_e32 v14, v14
	v_cvt_f32_i32_e32 v15, v15
	v_cvt_f32_i32_e32 v16, v16
	v_cvt_f32_i32_e32 v17, v17
	v_pk_mul_f32 v[142:143], v[222:223], v[188:189] op_sel_hi:[1,0]
	v_pk_mul_f32 v[144:145], v[224:225], v[188:189] op_sel_hi:[1,0]
	v_pk_fma_f32 v[154:155], v[142:143], v[14:15], v[206:207]
	v_pk_fma_f32 v[156:157], v[144:145], v[16:17], v[208:209]
	v_mul_f32_e32 v154, 0xbfb8aa3b, v154
	v_mul_f32_e32 v155, 0xbfb8aa3b, v155
	v_mul_f32_e32 v156, 0xbfb8aa3b, v156
	v_mul_f32_e32 v157, 0xbfb8aa3b, v157
	v_exp_f32_e32 v154, v154
	v_exp_f32_e32 v155, v155
	v_exp_f32_e32 v156, v156
	v_exp_f32_e32 v157, v157
	v_lshlrev_b32_e32 v146, 16, v170
	v_and_b32_e32 v147, 0xffff0000, v170
	v_lshlrev_b32_e32 v148, 16, v171
	v_and_b32_e32 v149, 0xffff0000, v171
	v_add_f32_e32 v154, 1.0, v154
	v_add_f32_e32 v155, 1.0, v155
	v_add_f32_e32 v156, 1.0, v156
	v_add_f32_e32 v157, 1.0, v157
	v_rcp_f32_e32 v154, v154
	v_rcp_f32_e32 v155, v155
	v_rcp_f32_e32 v156, v156
	v_rcp_f32_e32 v157, v157
	v_lshlrev_b32_e32 v150, 16, v178
	v_and_b32_e32 v151, 0xffff0000, v178
	v_lshlrev_b32_e32 v152, 16, v179
	v_and_b32_e32 v153, 0xffff0000, v179
	v_pk_fma_f32 v[14:15], v[154:155], v[150:151], v[146:147]
	v_pk_fma_f32 v[16:17], v[156:157], v[152:153], v[148:149]
	v_pk_mul_f32 v[194:195], v[14:15], v[14:15]
	v_pk_mul_f32 v[196:197], v[16:17], v[16:17]
	v_cvt_f32_i32_e32 v10, v10
	v_cvt_f32_i32_e32 v11, v11
	v_cvt_f32_i32_e32 v12, v12
	v_cvt_f32_i32_e32 v13, v13
	v_pk_mul_f32 v[142:143], v[226:227], v[188:189] op_sel_hi:[1,0]
	v_pk_mul_f32 v[144:145], v[228:229], v[188:189] op_sel_hi:[1,0]
	v_pk_fma_f32 v[154:155], v[142:143], v[10:11], v[210:211]
	v_pk_fma_f32 v[156:157], v[144:145], v[12:13], v[212:213]
	v_mul_f32_e32 v154, 0xbfb8aa3b, v154
	v_mul_f32_e32 v155, 0xbfb8aa3b, v155
	v_mul_f32_e32 v156, 0xbfb8aa3b, v156
	v_mul_f32_e32 v157, 0xbfb8aa3b, v157
	v_exp_f32_e32 v154, v154
	v_exp_f32_e32 v155, v155
	v_exp_f32_e32 v156, v156
	v_exp_f32_e32 v157, v157
	v_lshlrev_b32_e32 v146, 16, v172
	v_and_b32_e32 v147, 0xffff0000, v172
	v_lshlrev_b32_e32 v148, 16, v173
	v_and_b32_e32 v149, 0xffff0000, v173
	v_add_f32_e32 v154, 1.0, v154
	v_add_f32_e32 v155, 1.0, v155
	v_add_f32_e32 v156, 1.0, v156
	v_add_f32_e32 v157, 1.0, v157
	v_rcp_f32_e32 v154, v154
	v_rcp_f32_e32 v155, v155
	v_rcp_f32_e32 v156, v156
	v_rcp_f32_e32 v157, v157
	v_lshlrev_b32_e32 v150, 16, v180
	v_and_b32_e32 v151, 0xffff0000, v180
	v_lshlrev_b32_e32 v152, 16, v181
	v_and_b32_e32 v153, 0xffff0000, v181
	v_pk_fma_f32 v[10:11], v[154:155], v[150:151], v[146:147]
	v_pk_fma_f32 v[12:13], v[156:157], v[152:153], v[148:149]
	v_pk_fma_f32 v[194:195], v[10:11], v[10:11], v[194:195]
	v_pk_fma_f32 v[196:197], v[12:13], v[12:13], v[196:197]
	v_cvt_f32_i32_e32 v6, v6
	v_cvt_f32_i32_e32 v7, v7
	v_cvt_f32_i32_e32 v8, v8
	v_cvt_f32_i32_e32 v9, v9
	v_pk_mul_f32 v[142:143], v[230:231], v[188:189] op_sel_hi:[1,0]
	v_pk_mul_f32 v[144:145], v[232:233], v[188:189] op_sel_hi:[1,0]
	v_pk_fma_f32 v[154:155], v[142:143], v[6:7], v[214:215]
	v_pk_fma_f32 v[156:157], v[144:145], v[8:9], v[216:217]
	v_mul_f32_e32 v154, 0xbfb8aa3b, v154
	v_mul_f32_e32 v155, 0xbfb8aa3b, v155
	v_mul_f32_e32 v156, 0xbfb8aa3b, v156
	v_mul_f32_e32 v157, 0xbfb8aa3b, v157
	v_exp_f32_e32 v154, v154
	v_exp_f32_e32 v155, v155
	v_exp_f32_e32 v156, v156
	v_exp_f32_e32 v157, v157
	v_lshlrev_b32_e32 v146, 16, v174
	v_and_b32_e32 v147, 0xffff0000, v174
	v_lshlrev_b32_e32 v148, 16, v175
	v_and_b32_e32 v149, 0xffff0000, v175
	v_add_f32_e32 v154, 1.0, v154
	v_add_f32_e32 v155, 1.0, v155
	v_add_f32_e32 v156, 1.0, v156
	v_add_f32_e32 v157, 1.0, v157
	v_rcp_f32_e32 v154, v154
	v_rcp_f32_e32 v155, v155
	v_rcp_f32_e32 v156, v156
	v_rcp_f32_e32 v157, v157
	v_lshlrev_b32_e32 v150, 16, v182
	v_and_b32_e32 v151, 0xffff0000, v182
	v_lshlrev_b32_e32 v152, 16, v183
	v_and_b32_e32 v153, 0xffff0000, v183
	v_pk_fma_f32 v[6:7], v[154:155], v[150:151], v[146:147]
	v_pk_fma_f32 v[8:9], v[156:157], v[152:153], v[148:149]
	v_pk_fma_f32 v[194:195], v[6:7], v[6:7], v[194:195]
	v_pk_fma_f32 v[196:197], v[8:9], v[8:9], v[196:197]
	v_cvt_f32_i32_e32 v2, v2
	v_cvt_f32_i32_e32 v3, v3
	v_cvt_f32_i32_e32 v4, v4
	v_cvt_f32_i32_e32 v5, v5
	v_pk_mul_f32 v[142:143], v[234:235], v[188:189] op_sel_hi:[1,0]
	v_pk_mul_f32 v[144:145], v[236:237], v[188:189] op_sel_hi:[1,0]
	v_pk_fma_f32 v[154:155], v[142:143], v[2:3], v[218:219]
	v_pk_fma_f32 v[156:157], v[144:145], v[4:5], v[220:221]
	v_mul_f32_e32 v154, 0xbfb8aa3b, v154
	v_mul_f32_e32 v155, 0xbfb8aa3b, v155
	v_mul_f32_e32 v156, 0xbfb8aa3b, v156
	v_mul_f32_e32 v157, 0xbfb8aa3b, v157
	v_exp_f32_e32 v154, v154
	v_exp_f32_e32 v155, v155
	v_exp_f32_e32 v156, v156
	v_exp_f32_e32 v157, v157
	v_lshlrev_b32_e32 v146, 16, v176
	v_and_b32_e32 v147, 0xffff0000, v176
	v_lshlrev_b32_e32 v148, 16, v177
	v_and_b32_e32 v149, 0xffff0000, v177
	v_add_f32_e32 v154, 1.0, v154
	v_add_f32_e32 v155, 1.0, v155
	v_add_f32_e32 v156, 1.0, v156
	v_add_f32_e32 v157, 1.0, v157
	v_rcp_f32_e32 v154, v154
	v_rcp_f32_e32 v155, v155
	v_rcp_f32_e32 v156, v156
	v_rcp_f32_e32 v157, v157
	v_lshlrev_b32_e32 v150, 16, v184
	v_and_b32_e32 v151, 0xffff0000, v184
	v_lshlrev_b32_e32 v152, 16, v185
	v_and_b32_e32 v153, 0xffff0000, v185
	v_pk_fma_f32 v[2:3], v[154:155], v[150:151], v[146:147]
	v_pk_fma_f32 v[4:5], v[156:157], v[152:153], v[148:149]
	v_pk_fma_f32 v[194:195], v[2:3], v[2:3], v[194:195]
	v_pk_fma_f32 v[196:197], v[4:5], v[4:5], v[196:197]
	v_add_f32_e32 v194, v194, v195
	v_add_f32_e32 v196, v196, v197
	v_add_f32_e32 v194, v194, v196
	ds_bpermute_b32 v195, v58, v194
	s_waitcnt lgkmcnt(0)
	v_add_f32_e32 v194, v194, v195
	ds_bpermute_b32 v195, v59, v194
	s_waitcnt lgkmcnt(0)
	v_add_f32_e32 v194, v194, v195
	s_and_saveexec_b64 s[32:33], s[6:7]
	global_atomic_add_f32 v54, v194, s[70:71] offset:704
	s_or_b64 exec, exec, s[32:33]
	s_waitcnt vmcnt(0)
	s_barrier
; __device__ __forceinline__ void ph_final_norm(float* H, const float* __restrict__ rowss, const float* __restrict__ g, size_t gt, size_t NGT) {
;     ...
;         for (int k = 0; k < 8; ++k) { const size_t i = i0 + k * NGT; v[k] = h4[i]; rs[k] = rowss[i >> 10]; }
; #pragma unroll
;         for (int k = 0; k < 8; ++k) { const size_t i = i0 + k * NGT; const f32x4 gg = ((const f32x4*)g)[i & 1023]; h4[i] = v[k] * rsqrtf(rs[k] * (1.f / DM) + EPS) * gg; }
	s_load_dwordx2 s[100:101], s[92:93], 0xa8
	s_lshl_b32 s48, s98, 7
	s_add_u32 s50, s26, s48
	s_addc_u32 s51, s27, 0
	s_add_u32 s50, s50, 0x10000
	s_addc_u32 s51, s51, 0
	s_and_saveexec_b64 s[52:53], s[96:97]
	s_cbranch_execz .Lfz_poll_done
	v_mov_b32_e32 v60, 0
	v_mov_b32_e32 v61, 1
	global_atomic_add v60, v61, s[50:51]
	s_mov_b32 s49, 0
.Lfz_poll:
	global_load_dword v61, v60, s[50:51] sc1
	s_waitcnt vmcnt(0)
	v_readfirstlane_b32 s68, v61
	s_cmp_ge_u32 s68, 16
	s_cbranch_scc1 .Lfz_poll_done
	s_sleep 1
	s_add_i32 s49, s49, 1
	s_cmp_lt_u32 s49, 0x10000
	s_cbranch_scc1 .Lfz_poll
.Lfz_poll_done:
	s_or_b64 exec, exec, s[52:53]
	s_barrier
	global_load_dword v142, v54, s[70:71] sc1
	global_load_dword v144, v54, s[70:71] offset:64 sc1
	global_load_dword v146, v54, s[70:71] offset:128 sc1
	global_load_dword v148, v54, s[70:71] offset:192 sc1
	global_load_dword v150, v54, s[70:71] offset:512 sc1
	global_load_dword v152, v54, s[70:71] offset:576 sc1
	global_load_dword v154, v54, s[70:71] offset:640 sc1
	global_load_dword v156, v54, s[70:71] offset:704 sc1
	s_waitcnt lgkmcnt(0)
	s_lshl_b32 s48, s99, 10
	s_add_u32 s100, s100, s48
	s_addc_u32 s101, s101, 0
	global_load_dwordx4 v[206:209], v55, s[100:101]
	global_load_dwordx4 v[210:213], v55, s[100:101] offset:16
	global_load_dwordx4 v[214:217], v55, s[100:101] offset:512
	global_load_dwordx4 v[218:221], v55, s[100:101] offset:528
	s_mov_b64 s[90:91], s[84:85]
	s_waitcnt vmcnt(0)
	v_fmamk_f32 v142, v142, 0x39800000, v204
	v_fmamk_f32 v144, v144, 0x39800000, v204
	v_fmamk_f32 v146, v146, 0x39800000, v204
	v_fmamk_f32 v148, v148, 0x39800000, v204
	v_fmamk_f32 v150, v150, 0x39800000, v204
	v_fmamk_f32 v152, v152, 0x39800000, v204
	v_fmamk_f32 v154, v154, 0x39800000, v204
	v_fmamk_f32 v156, v156, 0x39800000, v204
	v_rsq_f32_e32 v142, v142
	v_rsq_f32_e32 v144, v144
	v_rsq_f32_e32 v146, v146
	v_rsq_f32_e32 v148, v148
	v_rsq_f32_e32 v150, v150
	v_rsq_f32_e32 v152, v152
	v_rsq_f32_e32 v154, v154
	v_rsq_f32_e32 v156, v156
	s_nop 0
	v_pk_mul_f32 v[50:51], v[50:51], v[142:143] op_sel_hi:[1,0]
	v_pk_mul_f32 v[52:53], v[52:53], v[142:143] op_sel_hi:[1,0]
	v_pk_mul_f32 v[50:51], v[50:51], v[206:207]
	v_pk_mul_f32 v[52:53], v[52:53], v[208:209]
	v_pk_mul_f32 v[138:139], v[138:139], v[142:143] op_sel_hi:[1,0]
	v_pk_mul_f32 v[140:141], v[140:141], v[142:143] op_sel_hi:[1,0]
	v_pk_mul_f32 v[138:139], v[138:139], v[210:211]
	v_pk_mul_f32 v[140:141], v[140:141], v[212:213]
	v_pk_mul_f32 v[134:135], v[134:135], v[142:143] op_sel_hi:[1,0]
	v_pk_mul_f32 v[136:137], v[136:137], v[142:143] op_sel_hi:[1,0]
	v_pk_mul_f32 v[134:135], v[134:135], v[214:215]
	v_pk_mul_f32 v[136:137], v[136:137], v[216:217]
	v_pk_mul_f32 v[130:131], v[130:131], v[142:143] op_sel_hi:[1,0]
	v_pk_mul_f32 v[132:133], v[132:133], v[142:143] op_sel_hi:[1,0]
	v_pk_mul_f32 v[130:131], v[130:131], v[218:219]
	v_pk_mul_f32 v[132:133], v[132:133], v[220:221]
	global_store_dwordx4 v57, v[50:53], s[90:91]
	global_store_dwordx4 v57, v[138:141], s[90:91] offset:16
	global_store_dwordx4 v57, v[134:137], s[90:91] offset:512
	global_store_dwordx4 v57, v[130:133], s[90:91] offset:528
	s_add_u32 s90, s90, 0x40000
	s_addc_u32 s91, s91, 0
	v_pk_mul_f32 v[126:127], v[126:127], v[144:145] op_sel_hi:[1,0]
	v_pk_mul_f32 v[128:129], v[128:129], v[144:145] op_sel_hi:[1,0]
	v_pk_mul_f32 v[126:127], v[126:127], v[206:207]
	v_pk_mul_f32 v[128:129], v[128:129], v[208:209]
	v_pk_mul_f32 v[122:123], v[122:123], v[144:145] op_sel_hi:[1,0]
	v_pk_mul_f32 v[124:125], v[124:125], v[144:145] op_sel_hi:[1,0]
	v_pk_mul_f32 v[122:123], v[122:123], v[210:211]
	v_pk_mul_f32 v[124:125], v[124:125], v[212:213]
	v_pk_mul_f32 v[118:119], v[118:119], v[144:145] op_sel_hi:[1,0]
	v_pk_mul_f32 v[120:121], v[120:121], v[144:145] op_sel_hi:[1,0]
	v_pk_mul_f32 v[118:119], v[118:119], v[214:215]
	v_pk_mul_f32 v[120:121], v[120:121], v[216:217]
	v_pk_mul_f32 v[114:115], v[114:115], v[144:145] op_sel_hi:[1,0]
	v_pk_mul_f32 v[116:117], v[116:117], v[144:145] op_sel_hi:[1,0]
	v_pk_mul_f32 v[114:115], v[114:115], v[218:219]
	v_pk_mul_f32 v[116:117], v[116:117], v[220:221]
	global_store_dwordx4 v57, v[126:129], s[90:91]
	global_store_dwordx4 v57, v[122:125], s[90:91] offset:16
	global_store_dwordx4 v57, v[118:121], s[90:91] offset:512
	global_store_dwordx4 v57, v[114:117], s[90:91] offset:528
	s_add_u32 s90, s90, 0x40000
	s_addc_u32 s91, s91, 0
	v_pk_mul_f32 v[110:111], v[110:111], v[146:147] op_sel_hi:[1,0]
	v_pk_mul_f32 v[112:113], v[112:113], v[146:147] op_sel_hi:[1,0]
	v_pk_mul_f32 v[110:111], v[110:111], v[206:207]
	v_pk_mul_f32 v[112:113], v[112:113], v[208:209]
	v_pk_mul_f32 v[106:107], v[106:107], v[146:147] op_sel_hi:[1,0]
	v_pk_mul_f32 v[108:109], v[108:109], v[146:147] op_sel_hi:[1,0]
	v_pk_mul_f32 v[106:107], v[106:107], v[210:211]
	v_pk_mul_f32 v[108:109], v[108:109], v[212:213]
	v_pk_mul_f32 v[102:103], v[102:103], v[146:147] op_sel_hi:[1,0]
	v_pk_mul_f32 v[104:105], v[104:105], v[146:147] op_sel_hi:[1,0]
	v_pk_mul_f32 v[102:103], v[102:103], v[214:215]
	v_pk_mul_f32 v[104:105], v[104:105], v[216:217]
	v_pk_mul_f32 v[98:99], v[98:99], v[146:147] op_sel_hi:[1,0]
	v_pk_mul_f32 v[100:101], v[100:101], v[146:147] op_sel_hi:[1,0]
	v_pk_mul_f32 v[98:99], v[98:99], v[218:219]
	v_pk_mul_f32 v[100:101], v[100:101], v[220:221]
	global_store_dwordx4 v57, v[110:113], s[90:91]
	global_store_dwordx4 v57, v[106:109], s[90:91] offset:16
	global_store_dwordx4 v57, v[102:105], s[90:91] offset:512
	global_store_dwordx4 v57, v[98:101], s[90:91] offset:528
	s_add_u32 s90, s90, 0x40000
	s_addc_u32 s91, s91, 0
	v_pk_mul_f32 v[94:95], v[94:95], v[148:149] op_sel_hi:[1,0]
; __device__ __forceinline__ void ph_final_norm(float* H, const float* __restrict__ rowss, const float* __restrict__ g, size_t gt, size_t NGT) {
;     ...
;         for (int k = 0; k < 8; ++k) { const size_t i = i0 + k * NGT; v[k] = h4[i]; rs[k] = rowss[i >> 10]; }
; #pragma unroll
;         for (int k = 0; k < 8; ++k) { const size_t i = i0 + k * NGT; const f32x4 gg = ((const f32x4*)g)[i & 1023]; h4[i] = v[k] * rsqrtf(rs[k] * (1.f / DM) + EPS) * gg; }
	v_pk_mul_f32 v[96:97], v[96:97], v[148:149] op_sel_hi:[1,0]
	v_pk_mul_f32 v[94:95], v[94:95], v[206:207]
	v_pk_mul_f32 v[96:97], v[96:97], v[208:209]
	v_pk_mul_f32 v[90:91], v[90:91], v[148:149] op_sel_hi:[1,0]
	v_pk_mul_f32 v[92:93], v[92:93], v[148:149] op_sel_hi:[1,0]
	v_pk_mul_f32 v[90:91], v[90:91], v[210:211]
	v_pk_mul_f32 v[92:93], v[92:93], v[212:213]
	v_pk_mul_f32 v[86:87], v[86:87], v[148:149] op_sel_hi:[1,0]
	v_pk_mul_f32 v[88:89], v[88:89], v[148:149] op_sel_hi:[1,0]
	v_pk_mul_f32 v[86:87], v[86:87], v[214:215]
	v_pk_mul_f32 v[88:89], v[88:89], v[216:217]
	v_pk_mul_f32 v[82:83], v[82:83], v[148:149] op_sel_hi:[1,0]
	v_pk_mul_f32 v[84:85], v[84:85], v[148:149] op_sel_hi:[1,0]
	v_pk_mul_f32 v[82:83], v[82:83], v[218:219]
	v_pk_mul_f32 v[84:85], v[84:85], v[220:221]
	global_store_dwordx4 v57, v[94:97], s[90:91]
	global_store_dwordx4 v57, v[90:93], s[90:91] offset:16
	global_store_dwordx4 v57, v[86:89], s[90:91] offset:512
	global_store_dwordx4 v57, v[82:85], s[90:91] offset:528
	s_add_u32 s90, s90, 0x140000
	s_addc_u32 s91, s91, 0
	v_pk_mul_f32 v[78:79], v[78:79], v[150:151] op_sel_hi:[1,0]
	v_pk_mul_f32 v[80:81], v[80:81], v[150:151] op_sel_hi:[1,0]
	v_pk_mul_f32 v[78:79], v[78:79], v[206:207]
	v_pk_mul_f32 v[80:81], v[80:81], v[208:209]
	v_pk_mul_f32 v[74:75], v[74:75], v[150:151] op_sel_hi:[1,0]
	v_pk_mul_f32 v[76:77], v[76:77], v[150:151] op_sel_hi:[1,0]
	v_pk_mul_f32 v[74:75], v[74:75], v[210:211]
	v_pk_mul_f32 v[76:77], v[76:77], v[212:213]
	v_pk_mul_f32 v[70:71], v[70:71], v[150:151] op_sel_hi:[1,0]
	v_pk_mul_f32 v[72:73], v[72:73], v[150:151] op_sel_hi:[1,0]
	v_pk_mul_f32 v[70:71], v[70:71], v[214:215]
	v_pk_mul_f32 v[72:73], v[72:73], v[216:217]
	v_pk_mul_f32 v[62:63], v[62:63], v[150:151] op_sel_hi:[1,0]
	v_pk_mul_f32 v[64:65], v[64:65], v[150:151] op_sel_hi:[1,0]
	v_pk_mul_f32 v[62:63], v[62:63], v[218:219]
	v_pk_mul_f32 v[64:65], v[64:65], v[220:221]
	global_store_dwordx4 v57, v[78:81], s[90:91]
	global_store_dwordx4 v57, v[74:77], s[90:91] offset:16
	global_store_dwordx4 v57, v[70:73], s[90:91] offset:512
	global_store_dwordx4 v57, v[62:65], s[90:91] offset:528
	s_add_u32 s90, s90, 0x40000
	s_addc_u32 s91, s91, 0
	v_pk_mul_f32 v[46:47], v[46:47], v[152:153] op_sel_hi:[1,0]
	v_pk_mul_f32 v[48:49], v[48:49], v[152:153] op_sel_hi:[1,0]
	v_pk_mul_f32 v[46:47], v[46:47], v[206:207]
	v_pk_mul_f32 v[48:49], v[48:49], v[208:209]
	v_pk_mul_f32 v[42:43], v[42:43], v[152:153] op_sel_hi:[1,0]
	v_pk_mul_f32 v[44:45], v[44:45], v[152:153] op_sel_hi:[1,0]
	v_pk_mul_f32 v[42:43], v[42:43], v[210:211]
	v_pk_mul_f32 v[44:45], v[44:45], v[212:213]
	v_pk_mul_f32 v[38:39], v[38:39], v[152:153] op_sel_hi:[1,0]
	v_pk_mul_f32 v[40:41], v[40:41], v[152:153] op_sel_hi:[1,0]
	v_pk_mul_f32 v[38:39], v[38:39], v[214:215]
	v_pk_mul_f32 v[40:41], v[40:41], v[216:217]
	v_pk_mul_f32 v[34:35], v[34:35], v[152:153] op_sel_hi:[1,0]
	v_pk_mul_f32 v[36:37], v[36:37], v[152:153] op_sel_hi:[1,0]
	v_pk_mul_f32 v[34:35], v[34:35], v[218:219]
	v_pk_mul_f32 v[36:37], v[36:37], v[220:221]
	global_store_dwordx4 v57, v[46:49], s[90:91]
	global_store_dwordx4 v57, v[42:45], s[90:91] offset:16
	global_store_dwordx4 v57, v[38:41], s[90:91] offset:512
	global_store_dwordx4 v57, v[34:37], s[90:91] offset:528
	s_add_u32 s90, s90, 0x40000
	s_addc_u32 s91, s91, 0
	v_pk_mul_f32 v[30:31], v[30:31], v[154:155] op_sel_hi:[1,0]
	v_pk_mul_f32 v[32:33], v[32:33], v[154:155] op_sel_hi:[1,0]
	v_pk_mul_f32 v[30:31], v[30:31], v[206:207]
	v_pk_mul_f32 v[32:33], v[32:33], v[208:209]
	v_pk_mul_f32 v[26:27], v[26:27], v[154:155] op_sel_hi:[1,0]
	v_pk_mul_f32 v[28:29], v[28:29], v[154:155] op_sel_hi:[1,0]
	v_pk_mul_f32 v[26:27], v[26:27], v[210:211]
	v_pk_mul_f32 v[28:29], v[28:29], v[212:213]
	v_pk_mul_f32 v[22:23], v[22:23], v[154:155] op_sel_hi:[1,0]
	v_pk_mul_f32 v[24:25], v[24:25], v[154:155] op_sel_hi:[1,0]
	v_pk_mul_f32 v[22:23], v[22:23], v[214:215]
	v_pk_mul_f32 v[24:25], v[24:25], v[216:217]
	v_pk_mul_f32 v[18:19], v[18:19], v[154:155] op_sel_hi:[1,0]
	v_pk_mul_f32 v[20:21], v[20:21], v[154:155] op_sel_hi:[1,0]
	v_pk_mul_f32 v[18:19], v[18:19], v[218:219]
	v_pk_mul_f32 v[20:21], v[20:21], v[220:221]
	global_store_dwordx4 v57, v[30:33], s[90:91]
	global_store_dwordx4 v57, v[26:29], s[90:91] offset:16
	global_store_dwordx4 v57, v[22:25], s[90:91] offset:512
	global_store_dwordx4 v57, v[18:21], s[90:91] offset:528
	s_add_u32 s90, s90, 0x40000
	s_addc_u32 s91, s91, 0
	v_pk_mul_f32 v[14:15], v[14:15], v[156:157] op_sel_hi:[1,0]
	v_pk_mul_f32 v[16:17], v[16:17], v[156:157] op_sel_hi:[1,0]
	v_pk_mul_f32 v[14:15], v[14:15], v[206:207]
	v_pk_mul_f32 v[16:17], v[16:17], v[208:209]
	v_pk_mul_f32 v[10:11], v[10:11], v[156:157] op_sel_hi:[1,0]
	v_pk_mul_f32 v[12:13], v[12:13], v[156:157] op_sel_hi:[1,0]
	v_pk_mul_f32 v[10:11], v[10:11], v[210:211]
	v_pk_mul_f32 v[12:13], v[12:13], v[212:213]
	v_pk_mul_f32 v[6:7], v[6:7], v[156:157] op_sel_hi:[1,0]
	v_pk_mul_f32 v[8:9], v[8:9], v[156:157] op_sel_hi:[1,0]
	v_pk_mul_f32 v[6:7], v[6:7], v[214:215]
	v_pk_mul_f32 v[8:9], v[8:9], v[216:217]
	v_pk_mul_f32 v[2:3], v[2:3], v[156:157] op_sel_hi:[1,0]
	v_pk_mul_f32 v[4:5], v[4:5], v[156:157] op_sel_hi:[1,0]
	v_pk_mul_f32 v[2:3], v[2:3], v[218:219]
	v_pk_mul_f32 v[4:5], v[4:5], v[220:221]
	global_store_dwordx4 v57, v[14:17], s[90:91]
	global_store_dwordx4 v57, v[10:13], s[90:91] offset:16
	global_store_dwordx4 v57, v[6:9], s[90:91] offset:512
	global_store_dwordx4 v57, v[2:5], s[90:91] offset:528
	s_nop 1
	s_andn2_b64 vcc, exec, s[8:9]
	s_mov_b64 s[8:9], -1
	s_cbranch_vccnz .LBB0_1449
	s_andn2_b64 vcc, exec, s[20:21]
	s_cbranch_vccnz .LBB0_1448
	s_barrier
	s_branch .LBB0_1448

; #define SEAM(k) do { if (IN(k) && IN((k) + 1)) xcd_barrier(bar); } while (0)
; __global__ void __launch_bounds__(512, 2) k_fwd(Args a_unused) {
;     ...
;     SEAM(8);
;     if (IN(9)) { PH_IDS(); ph_final_norm(ap->out, ctl + CW_RSS3, ap->in[21], gt, NGT); }
.LBB0_1480:
.LBB0_1538:
	s_endpgm

; __global__ void __launch_bounds__(512, 2) k_fwd(Args a_unused) {
	.amdhsa_kernel _Z5k_fwd4Args
		.amdhsa_group_segment_fixed_size 0
		.amdhsa_private_segment_fixed_size 0
		.amdhsa_kernarg_size 464
		.amdhsa_user_sgpr_count 2
		.amdhsa_user_sgpr_dispatch_ptr 0
		.amdhsa_user_sgpr_queue_ptr 0
		.amdhsa_user_sgpr_kernarg_segment_ptr 1
		.amdhsa_user_sgpr_dispatch_id 0
		.amdhsa_user_sgpr_kernarg_preload_length 0
		.amdhsa_user_sgpr_kernarg_preload_offset 0
		.amdhsa_user_sgpr_private_segment_size 0
		.amdhsa_uses_dynamic_stack 0
		.amdhsa_enable_private_segment 0
		.amdhsa_system_sgpr_workgroup_id_x 1
		.amdhsa_system_sgpr_workgroup_id_y 0
		.amdhsa_system_sgpr_workgroup_id_z 0
		.amdhsa_system_sgpr_workgroup_info 0
		.amdhsa_system_vgpr_workitem_id 0
		.amdhsa_next_free_vgpr 255
		.amdhsa_next_free_sgpr 102
		.amdhsa_accum_offset 256
		.amdhsa_reserve_vcc 1
		.amdhsa_float_round_mode_32 0
		.amdhsa_float_round_mode_16_64 0
		.amdhsa_float_denorm_mode_32 3
		.amdhsa_float_denorm_mode_16_64 3
		.amdhsa_dx10_clamp 1
		.amdhsa_ieee_mode 1
		.amdhsa_fp16_overflow 0
		.amdhsa_tg_split 0
		.amdhsa_exception_fp_ieee_invalid_op 0
		.amdhsa_exception_fp_denorm_src 0
		.amdhsa_exception_fp_ieee_div_zero 0
		.amdhsa_exception_fp_ieee_overflow 0
		.amdhsa_exception_fp_ieee_underflow 0
		.amdhsa_exception_fp_ieee_inexact 0
		.amdhsa_exception_int_div_zero 0
	.end_amdhsa_kernel
